# loop-edge edit: K-loop counter/pointer SALU and exit test moved ahead of the loop-back barrier in the six GEMM K-loops (only the branch stays behind it); otherwise v19
# baseline (speedup 1.0000x reference)
; #define PG8_STAGE(bufoff, gbase, voff) do { _Pragma("unroll") for (int _i = 0; _i < 2; ++_i) _Pragma("unroll") for (int _r = 0; _r < PG8_NREP; ++_r) \
;         __builtin_amdgcn_global_load_lds((const unsigned*)((const char*)(gbase) + (voff)[_i]), (PG8_LAS unsigned*)(lds + (bufoff) + ldsw + _i * 8192), 16, 0, 0); } while (0)
; #define PG8_LDA(dst, b, h) do { _Pragma("unroll") for (int m = 0; m < 4; ++m) _Pragma("unroll") for (int k = 0; k < 2; ++k) { dst[m][k] = *(const PG8_LAS bf16x8*)(lds + PG8_SA(b, h) + aoff + m * 2048 + k * 1024); PG8_DUP((unsigned)(uintptr_t)(lds + PG8_SA(b, h) + aoff + m * 2048 + k * 1024)); } } while (0)
; #define PG8_LDB(dst, b, h) do { _Pragma("unroll") for (int n = 0; n < 2; ++n) _Pragma("unroll") for (int k = 0; k < 2; ++k) { dst[n][k] = *(const PG8_LAS bf16x8*)(lds + PG8_SB(b, h) + boff + n * 2048 + k * 1024); PG8_DUP((unsigned)(uintptr_t)(lds + PG8_SB(b, h) + boff + n * 2048 + k * 1024)); } } while (0)
; #define PG8_MMA(ai, bj, At, Bt) do { __builtin_amdgcn_s_setprio(1); _Pragma("unroll") for (int m = 0; m < 4; ++m) _Pragma("unroll") for (int n = 0; n < 2; ++n) _Pragma("unroll") for (int k = 0; k < 2; ++k) \
;         acc[ai][bj][m][n] = __builtin_amdgcn_mfma_f32_16x16x32_bf16(Bt[n][k], At[m][k], acc[ai][bj][m][n], 0, 0, 0); __builtin_amdgcn_s_setprio(0); } while (0)
; template <class Epi, class Sched, bool ALIGN_EPI = false, bool SP2 = false>
; __device__ __forceinline__ void gemm_phase(PG8_LAS unsigned char* lds, const Gemm g, const Sched& S, const Epi& E) {
;     ...
;             const bool last = (t == nt - 2);
;             const char* a1 = cA + (size_t)(t + 1) * kstep;
;             const char* a2 = last ? nA : cA + (size_t)(t + 2) * kstep; const char* b2 = last ? nB : cB + (size_t)(t + 2) * kstep;
;             const char* a3 = a2 + kstep; const char* b3 = b2 + kstep;
;             if (last && has_next) S.a_ready(nxt);
;             if constexpr (SP2) {
;     ...
;             if (Epi::PERM && sizeof(Epi) && TEST_DRAIN) PG8_WAIT_V(0);
;     ...
;             PG8_LDB(B0, 0, 0); PG8_LDB(B1, 0, 1); PG8_SCHED; PG8_LDA(At, 0, 0); PG8_STAGE(PG8_SA(1, 1), a1 + hstepA, voffA);
;             PG8_WAIT_V(8); PG8_WAIT_L(0); PG8_BAR; PG8_MMA(0, 0, At, B0); PG8_MMA(0, 1, At, B1); PG8_BAR; PG8_SCHED;
;             PG8_LDA(At, 0, 1); PG8_STAGE(PG8_SB(0, 0), b2, voffB); PG8_STAGE(PG8_SB(0, 1), b2 + hstepB, voffB); PG8_STAGE(PG8_SA(0, 0), a2, voffA);
.LBB0_156:
	s_add_u32 s26, s44, 0xfff80080
	s_addc_u32 s27, s45, -1
	s_add_i32 s28, 0, 0x10000
	s_cmp_eq_u32 s25, 28
	s_cselect_b32 s95, s15, s27
	s_cselect_b32 s94, s86, s26
	s_cselect_b32 s47, s63, s24
	s_cselect_b32 s46, vcc_lo, vcc_hi
	s_add_i32 s29, 0, 0x14000
	v_add_u32_e32 v76, s28, v161
	v_add_u32_e32 v158, s29, v161
	ds_read_b128 v[60:63], v76
	ds_read_b128 v[68:71], v76 offset:1024
	ds_read_b128 v[72:75], v76 offset:2048
	ds_read_b128 v[76:79], v76 offset:3072
	ds_read_b128 v[154:157], v158
	ds_read_b128 v[164:167], v158 offset:1024
	ds_read_b128 v[168:171], v158 offset:2048
	ds_read_b128 v[172:175], v158 offset:3072
	v_lshl_add_u64 v[158:159], s[44:45], 0, v[150:151]
	s_add_i32 m0, s17, 0xc000
	ds_read_b128 v[176:179], v163
	ds_read_b128 v[180:183], v163 offset:1024
	ds_read_b128 v[184:187], v163 offset:2048
	ds_read_b128 v[188:191], v163 offset:3072
	ds_read_b128 v[210:213], v163 offset:4096
	ds_read_b128 v[214:217], v163 offset:5120
	ds_read_b128 v[218:221], v163 offset:6144
	ds_read_b128 v[222:225], v163 offset:7168
	global_load_lds_dwordx4 v[158:159], off
	v_lshl_add_u64 v[158:159], s[44:45], 0, v[152:153]
	s_add_i32 m0, s17, 0xe000
	s_nop 0
	global_load_lds_dwordx4 v[158:159], off
	s_waitcnt vmcnt(8)
	s_waitcnt lgkmcnt(0)
	s_barrier
	s_setprio 1
	s_waitcnt lgkmcnt(0)
	v_mfma_f32_16x16x32_bf16 v[140:143], v[60:63], v[176:179], v[140:143]
	v_mfma_f32_16x16x32_bf16 v[136:139], v[72:75], v[176:179], v[136:139]
	v_mfma_f32_16x16x32_bf16 v[124:127], v[60:63], v[184:187], v[124:127]
	v_mfma_f32_16x16x32_bf16 v[120:123], v[72:75], v[184:187], v[120:123]
	v_mfma_f32_16x16x32_bf16 v[108:111], v[60:63], v[210:213], v[108:111]
	v_mfma_f32_16x16x32_bf16 v[104:107], v[72:75], v[210:213], v[104:107]
	v_mfma_f32_16x16x32_bf16 v[92:95], v[60:63], v[218:221], v[92:95]
	v_mfma_f32_16x16x32_bf16 v[88:91], v[72:75], v[218:221], v[88:91]
	v_mfma_f32_16x16x32_bf16 v[140:143], v[68:71], v[180:183], v[140:143]
	v_mfma_f32_16x16x32_bf16 v[136:139], v[76:79], v[180:183], v[136:139]
	v_mfma_f32_16x16x32_bf16 v[124:127], v[68:71], v[188:191], v[124:127]
	v_mfma_f32_16x16x32_bf16 v[120:123], v[76:79], v[188:191], v[120:123]
	v_mfma_f32_16x16x32_bf16 v[108:111], v[68:71], v[214:217], v[108:111]
	v_mfma_f32_16x16x32_bf16 v[104:107], v[76:79], v[214:217], v[104:107]
	v_mfma_f32_16x16x32_bf16 v[92:95], v[68:71], v[222:225], v[92:95]
	v_mfma_f32_16x16x32_bf16 v[88:91], v[76:79], v[222:225], v[88:91]
	s_setprio 0
	s_setprio 1
	v_mfma_f32_16x16x32_bf16 v[132:135], v[154:157], v[176:179], v[132:135]
	v_mfma_f32_16x16x32_bf16 v[128:131], v[168:171], v[176:179], v[128:131]
	v_mfma_f32_16x16x32_bf16 v[116:119], v[154:157], v[184:187], v[116:119]
	v_mfma_f32_16x16x32_bf16 v[112:115], v[168:171], v[184:187], v[112:115]
	v_mfma_f32_16x16x32_bf16 v[100:103], v[154:157], v[210:213], v[100:103]
	v_mfma_f32_16x16x32_bf16 v[96:99], v[168:171], v[210:213], v[96:99]
	v_mfma_f32_16x16x32_bf16 v[84:87], v[154:157], v[218:221], v[84:87]
	v_mfma_f32_16x16x32_bf16 v[80:83], v[168:171], v[218:221], v[80:83]
	v_mfma_f32_16x16x32_bf16 v[132:135], v[164:167], v[180:183], v[132:135]
	v_mfma_f32_16x16x32_bf16 v[128:131], v[172:175], v[180:183], v[128:131]
	v_mfma_f32_16x16x32_bf16 v[116:119], v[164:167], v[188:191], v[116:119]
	v_mfma_f32_16x16x32_bf16 v[112:115], v[172:175], v[188:191], v[112:115]
	v_mfma_f32_16x16x32_bf16 v[100:103], v[164:167], v[214:217], v[100:103]
	v_mfma_f32_16x16x32_bf16 v[96:99], v[172:175], v[214:217], v[96:99]
	v_mfma_f32_16x16x32_bf16 v[84:87], v[164:167], v[222:225], v[84:87]
	v_mfma_f32_16x16x32_bf16 v[80:83], v[172:175], v[222:225], v[80:83]
	s_setprio 0
	s_barrier
	s_add_i32 s26, s28, s16
	v_lshl_add_u64 v[158:159], s[46:47], 0, v[192:193]
	s_mov_b32 m0, s26
	ds_read_b128 v[176:179], v163 offset:16384
	ds_read_b128 v[180:183], v163 offset:17408
	ds_read_b128 v[184:187], v163 offset:18432
	ds_read_b128 v[188:191], v163 offset:19456
	ds_read_b128 v[210:213], v163 offset:20480
	ds_read_b128 v[214:217], v163 offset:21504
	ds_read_b128 v[218:221], v163 offset:22528
	ds_read_b128 v[222:225], v163 offset:23552
	global_load_lds_dwordx4 v[158:159], off
	s_add_i32 m0, s26, 0x2000
	s_add_u32 s26, s46, 0x80000
	v_lshl_add_u64 v[194:195], s[46:47], 0, v[144:145]
	s_addc_u32 s27, s47, 0
	s_add_i32 s28, s29, s16
	global_load_lds_dwordx4 v[194:195], off
	v_lshl_add_u64 v[196:197], s[26:27], 0, v[192:193]
	s_mov_b32 m0, s28
	v_lshl_add_u64 v[200:201], s[94:95], 0, v[146:147]
	global_load_lds_dwordx4 v[196:197], off
	v_lshl_add_u64 v[196:197], s[26:27], 0, v[144:145]
	s_add_i32 m0, s28, 0x2000
	s_nop 0
	global_load_lds_dwordx4 v[196:197], off
	v_lshl_add_u64 v[196:197], s[94:95], 0, v[148:149]
	s_mov_b32 m0, s17
	s_nop 0
	global_load_lds_dwordx4 v[196:197], off
	s_mov_b32 m0, s18
	s_nop 0
	global_load_lds_dwordx4 v[200:201], off
	s_waitcnt vmcnt(8)
	s_waitcnt lgkmcnt(0)
	s_barrier
; #define PG8_STAGE(bufoff, gbase, voff) do { _Pragma("unroll") for (int _i = 0; _i < 2; ++_i) _Pragma("unroll") for (int _r = 0; _r < PG8_NREP; ++_r) \
;         __builtin_amdgcn_global_load_lds((const unsigned*)((const char*)(gbase) + (voff)[_i]), (PG8_LAS unsigned*)(lds + (bufoff) + ldsw + _i * 8192), 16, 0, 0); } while (0)
; #define PG8_LDA(dst, b, h) do { _Pragma("unroll") for (int m = 0; m < 4; ++m) _Pragma("unroll") for (int k = 0; k < 2; ++k) { dst[m][k] = *(const PG8_LAS bf16x8*)(lds + PG8_SA(b, h) + aoff + m * 2048 + k * 1024); PG8_DUP((unsigned)(uintptr_t)(lds + PG8_SA(b, h) + aoff + m * 2048 + k * 1024)); } } while (0)
; #define PG8_LDB(dst, b, h) do { _Pragma("unroll") for (int n = 0; n < 2; ++n) _Pragma("unroll") for (int k = 0; k < 2; ++k) { dst[n][k] = *(const PG8_LAS bf16x8*)(lds + PG8_SB(b, h) + boff + n * 2048 + k * 1024); PG8_DUP((unsigned)(uintptr_t)(lds + PG8_SB(b, h) + boff + n * 2048 + k * 1024)); } } while (0)
; #define PG8_MMA(ai, bj, At, Bt) do { __builtin_amdgcn_s_setprio(1); _Pragma("unroll") for (int m = 0; m < 4; ++m) _Pragma("unroll") for (int n = 0; n < 2; ++n) _Pragma("unroll") for (int k = 0; k < 2; ++k) \
;         acc[ai][bj][m][n] = __builtin_amdgcn_mfma_f32_16x16x32_bf16(Bt[n][k], At[m][k], acc[ai][bj][m][n], 0, 0, 0); __builtin_amdgcn_s_setprio(0); } while (0)
; #define PG8_WAIT_V(n) do { if ((n) == 0) asm volatile("s_waitcnt vmcnt(0)" ::: "memory"); else if ((n) == 2) asm volatile("s_waitcnt vmcnt(4)" ::: "memory"); else if ((n) == 4) asm volatile("s_waitcnt vmcnt(8)" ::: "memory"); \
;     else if ((n) == 6) asm volatile("s_waitcnt vmcnt(12)" ::: "memory"); else asm volatile("s_waitcnt vmcnt(16)" ::: "memory"); } while (0)
; #define PG8_WAIT_V(n) asm volatile("s_waitcnt vmcnt(" #n ")" ::: "memory")
; #define PG8_BAR __builtin_amdgcn_s_barrier()
; template <class Epi, class Sched, bool ALIGN_EPI = false, bool SP2 = false>
; __device__ __forceinline__ void gemm_phase(PG8_LAS unsigned char* lds, const Gemm g, const Sched& S, const Epi& E) {
;     ...
;             PG8_WAIT_V(8); PG8_WAIT_L(0); PG8_BAR; PG8_MMA(1, 0, At, B0); PG8_MMA(1, 1, At, B1); PG8_BAR; PG8_SCHED;
;             PG8_LDB(B0, 1, 0); PG8_LDB(B1, 1, 1); PG8_SCHED; PG8_LDA(At, 1, 0); PG8_STAGE(PG8_SA(0, 1), a2 + hstepA, voffA);
;             PG8_WAIT_V(8); PG8_WAIT_L(0); PG8_BAR; PG8_MMA(0, 0, At, B0); PG8_MMA(0, 1, At, B1); PG8_BAR; PG8_SCHED;
	s_setprio 1
	s_waitcnt lgkmcnt(0)
	v_mfma_f32_16x16x32_bf16 v[64:67], v[60:63], v[176:179], v[64:67]
	v_mfma_f32_16x16x32_bf16 v[56:59], v[72:75], v[176:179], v[56:59]
	v_mfma_f32_16x16x32_bf16 v[44:47], v[60:63], v[184:187], v[44:47]
	v_mfma_f32_16x16x32_bf16 v[40:43], v[72:75], v[184:187], v[40:43]
	v_mfma_f32_16x16x32_bf16 v[28:31], v[60:63], v[210:213], v[28:31]
	v_mfma_f32_16x16x32_bf16 v[24:27], v[72:75], v[210:213], v[24:27]
	v_mfma_f32_16x16x32_bf16 v[12:15], v[60:63], v[218:221], v[12:15]
	v_mfma_f32_16x16x32_bf16 v[8:11], v[72:75], v[218:221], v[8:11]
	v_mfma_f32_16x16x32_bf16 v[64:67], v[68:71], v[180:183], v[64:67]
	v_mfma_f32_16x16x32_bf16 v[56:59], v[76:79], v[180:183], v[56:59]
	v_mfma_f32_16x16x32_bf16 v[44:47], v[68:71], v[188:191], v[44:47]
	v_mfma_f32_16x16x32_bf16 v[40:43], v[76:79], v[188:191], v[40:43]
	v_mfma_f32_16x16x32_bf16 v[28:31], v[68:71], v[214:217], v[28:31]
	v_mfma_f32_16x16x32_bf16 v[24:27], v[76:79], v[214:217], v[24:27]
	v_mfma_f32_16x16x32_bf16 v[12:15], v[68:71], v[222:225], v[12:15]
	v_mfma_f32_16x16x32_bf16 v[8:11], v[76:79], v[222:225], v[8:11]
	s_setprio 0
	s_setprio 1
	v_mfma_f32_16x16x32_bf16 v[52:55], v[154:157], v[176:179], v[52:55]
	v_mfma_f32_16x16x32_bf16 v[48:51], v[168:171], v[176:179], v[48:51]
	v_mfma_f32_16x16x32_bf16 v[36:39], v[154:157], v[184:187], v[36:39]
	v_mfma_f32_16x16x32_bf16 v[32:35], v[168:171], v[184:187], v[32:35]
	v_mfma_f32_16x16x32_bf16 v[20:23], v[154:157], v[210:213], v[20:23]
	v_mfma_f32_16x16x32_bf16 v[16:19], v[168:171], v[210:213], v[16:19]
	v_mfma_f32_16x16x32_bf16 v[4:7], v[154:157], v[218:221], v[4:7]
	v_mfma_f32_16x16x32_bf16 v[0:3], v[168:171], v[218:221], v[0:3]
	v_mfma_f32_16x16x32_bf16 v[52:55], v[164:167], v[180:183], v[52:55]
	v_mfma_f32_16x16x32_bf16 v[48:51], v[172:175], v[180:183], v[48:51]
	v_mfma_f32_16x16x32_bf16 v[36:39], v[164:167], v[188:191], v[36:39]
	v_mfma_f32_16x16x32_bf16 v[32:35], v[172:175], v[188:191], v[32:35]
	v_mfma_f32_16x16x32_bf16 v[20:23], v[164:167], v[214:217], v[20:23]
	v_mfma_f32_16x16x32_bf16 v[16:19], v[172:175], v[214:217], v[16:19]
	v_mfma_f32_16x16x32_bf16 v[4:7], v[164:167], v[222:225], v[4:7]
	v_mfma_f32_16x16x32_bf16 v[0:3], v[172:175], v[222:225], v[0:3]
	s_setprio 0
	s_barrier
	s_add_i32 s28, 0, 0x18000
	s_add_i32 s29, 0, 0x1c000
	v_add_u32_e32 v76, s28, v161
	v_add_u32_e32 v172, s29, v161
	ds_read_b128 v[60:63], v76
	ds_read_b128 v[68:71], v76 offset:1024
	ds_read_b128 v[72:75], v76 offset:2048
	ds_read_b128 v[76:79], v76 offset:3072
	ds_read_b128 v[154:157], v172
	ds_read_b128 v[164:167], v172 offset:1024
	ds_read_b128 v[168:171], v172 offset:2048
	ds_read_b128 v[172:175], v172 offset:3072
	s_add_u32 s26, s94, 0x80000
	s_addc_u32 s27, s95, 0
	s_mov_b32 m0, s19
	v_lshl_add_u64 v[226:227], s[26:27], 0, v[148:149]
	ds_read_b128 v[176:179], v163 offset:32768
	ds_read_b128 v[180:183], v163 offset:33792
	ds_read_b128 v[184:187], v163 offset:34816
	ds_read_b128 v[188:191], v163 offset:35840
	ds_read_b128 v[210:213], v163 offset:36864
	ds_read_b128 v[214:217], v163 offset:37888
	ds_read_b128 v[218:221], v163 offset:38912
	ds_read_b128 v[222:225], v163 offset:39936
	global_load_lds_dwordx4 v[226:227], off
	v_lshl_add_u64 v[226:227], s[26:27], 0, v[146:147]
	s_mov_b32 m0, s20
	s_nop 0
	global_load_lds_dwordx4 v[226:227], off
	s_waitcnt vmcnt(8)
	s_waitcnt lgkmcnt(0)
	s_barrier
	s_setprio 1
	s_waitcnt lgkmcnt(0)
	v_mfma_f32_16x16x32_bf16 v[140:143], v[60:63], v[176:179], v[140:143]
	v_mfma_f32_16x16x32_bf16 v[136:139], v[72:75], v[176:179], v[136:139]
	v_mfma_f32_16x16x32_bf16 v[124:127], v[60:63], v[184:187], v[124:127]
	v_mfma_f32_16x16x32_bf16 v[120:123], v[72:75], v[184:187], v[120:123]
	v_mfma_f32_16x16x32_bf16 v[108:111], v[60:63], v[210:213], v[108:111]
	v_mfma_f32_16x16x32_bf16 v[104:107], v[72:75], v[210:213], v[104:107]
	v_mfma_f32_16x16x32_bf16 v[92:95], v[60:63], v[218:221], v[92:95]
	v_mfma_f32_16x16x32_bf16 v[88:91], v[72:75], v[218:221], v[88:91]
	v_mfma_f32_16x16x32_bf16 v[140:143], v[68:71], v[180:183], v[140:143]
	v_mfma_f32_16x16x32_bf16 v[136:139], v[76:79], v[180:183], v[136:139]
	v_mfma_f32_16x16x32_bf16 v[124:127], v[68:71], v[188:191], v[124:127]
	v_mfma_f32_16x16x32_bf16 v[120:123], v[76:79], v[188:191], v[120:123]
	v_mfma_f32_16x16x32_bf16 v[108:111], v[68:71], v[214:217], v[108:111]
	v_mfma_f32_16x16x32_bf16 v[104:107], v[76:79], v[214:217], v[104:107]
	v_mfma_f32_16x16x32_bf16 v[92:95], v[68:71], v[222:225], v[92:95]
	v_mfma_f32_16x16x32_bf16 v[88:91], v[76:79], v[222:225], v[88:91]
	s_setprio 0
	s_setprio 1
	v_mfma_f32_16x16x32_bf16 v[132:135], v[154:157], v[176:179], v[132:135]
	v_mfma_f32_16x16x32_bf16 v[128:131], v[168:171], v[176:179], v[128:131]
	v_mfma_f32_16x16x32_bf16 v[116:119], v[154:157], v[184:187], v[116:119]
	v_mfma_f32_16x16x32_bf16 v[112:115], v[168:171], v[184:187], v[112:115]
	v_mfma_f32_16x16x32_bf16 v[100:103], v[154:157], v[210:213], v[100:103]
	v_mfma_f32_16x16x32_bf16 v[96:99], v[168:171], v[210:213], v[96:99]
	v_mfma_f32_16x16x32_bf16 v[84:87], v[154:157], v[218:221], v[84:87]
	v_mfma_f32_16x16x32_bf16 v[80:83], v[168:171], v[218:221], v[80:83]
	v_mfma_f32_16x16x32_bf16 v[132:135], v[164:167], v[180:183], v[132:135]
	v_mfma_f32_16x16x32_bf16 v[128:131], v[172:175], v[180:183], v[128:131]
	v_mfma_f32_16x16x32_bf16 v[116:119], v[164:167], v[188:191], v[116:119]
	v_mfma_f32_16x16x32_bf16 v[112:115], v[172:175], v[188:191], v[112:115]
	v_mfma_f32_16x16x32_bf16 v[100:103], v[164:167], v[214:217], v[100:103]
	v_mfma_f32_16x16x32_bf16 v[96:99], v[172:175], v[214:217], v[96:99]
	v_mfma_f32_16x16x32_bf16 v[84:87], v[164:167], v[222:225], v[84:87]
	v_mfma_f32_16x16x32_bf16 v[80:83], v[172:175], v[222:225], v[80:83]
	s_setprio 0
	s_barrier
; #define PG8_STAGE(bufoff, gbase, voff) do { _Pragma("unroll") for (int _i = 0; _i < 2; ++_i) _Pragma("unroll") for (int _r = 0; _r < PG8_NREP; ++_r) \
;         __builtin_amdgcn_global_load_lds((const unsigned*)((const char*)(gbase) + (voff)[_i]), (PG8_LAS unsigned*)(lds + (bufoff) + ldsw + _i * 8192), 16, 0, 0); } while (0)
; #define PG8_LDA(dst, b, h) do { _Pragma("unroll") for (int m = 0; m < 4; ++m) _Pragma("unroll") for (int k = 0; k < 2; ++k) { dst[m][k] = *(const PG8_LAS bf16x8*)(lds + PG8_SA(b, h) + aoff + m * 2048 + k * 1024); PG8_DUP((unsigned)(uintptr_t)(lds + PG8_SA(b, h) + aoff + m * 2048 + k * 1024)); } } while (0)
; #define PG8_MMA(ai, bj, At, Bt) do { __builtin_amdgcn_s_setprio(1); _Pragma("unroll") for (int m = 0; m < 4; ++m) _Pragma("unroll") for (int n = 0; n < 2; ++n) _Pragma("unroll") for (int k = 0; k < 2; ++k) \
;         acc[ai][bj][m][n] = __builtin_amdgcn_mfma_f32_16x16x32_bf16(Bt[n][k], At[m][k], acc[ai][bj][m][n], 0, 0, 0); __builtin_amdgcn_s_setprio(0); } while (0)
; #define PG8_WAIT_V(n) do { if ((n) == 0) asm volatile("s_waitcnt vmcnt(0)" ::: "memory"); else if ((n) == 2) asm volatile("s_waitcnt vmcnt(4)" ::: "memory"); else if ((n) == 4) asm volatile("s_waitcnt vmcnt(8)" ::: "memory"); \
;     else if ((n) == 6) asm volatile("s_waitcnt vmcnt(12)" ::: "memory"); else asm volatile("s_waitcnt vmcnt(16)" ::: "memory"); } while (0)
; #define PG8_WAIT_V(n) asm volatile("s_waitcnt vmcnt(" #n ")" ::: "memory")
; #define PG8_WAIT_L(n) asm volatile("s_waitcnt lgkmcnt(" #n ")" ::: "memory")
; #define PG8_BAR __builtin_amdgcn_s_barrier()
; #define PG8_SCHED __builtin_amdgcn_sched_barrier(0)
; template <class Epi, class Sched, bool ALIGN_EPI = false, bool SP2 = false>
; __device__ __forceinline__ void gemm_phase(PG8_LAS unsigned char* lds, const Gemm g, const Sched& S, const Epi& E) {
;     ...
;             PG8_LDA(At, 1, 1); PG8_STAGE(PG8_SB(1, 0), b3, voffB); PG8_STAGE(PG8_SB(1, 1), b3 + hstepB, voffB); PG8_STAGE(PG8_SA(1, 0), a3, voffA);
;             PG8_WAIT_V(8); PG8_WAIT_L(0); PG8_BAR; PG8_MMA(1, 0, At, B0); PG8_MMA(1, 1, At, B1); PG8_BAR; PG8_SCHED;
;     ...
;         if constexpr (ALIGN_EPI) { if (wr == 0) PG8_BAR; }
	s_add_i32 s26, s28, s16
	v_lshl_add_u64 v[158:159], v[158:159], 0, s[68:69]
	s_mov_b32 m0, s26
	ds_read_b128 v[176:179], v163 offset:49152
	ds_read_b128 v[180:183], v163 offset:50176
	ds_read_b128 v[184:187], v163 offset:51200
	ds_read_b128 v[188:191], v163 offset:52224
	ds_read_b128 v[210:213], v163 offset:53248
	ds_read_b128 v[214:217], v163 offset:54272
	ds_read_b128 v[218:221], v163 offset:55296
	ds_read_b128 v[222:225], v163 offset:56320
	global_load_lds_dwordx4 v[158:159], off
	s_add_i32 m0, s26, 0x2000
	s_add_u32 s26, s46, 0x80080
	v_lshl_add_u64 v[158:159], v[194:195], 0, s[68:69]
	s_addc_u32 s27, s47, 0
	s_add_i32 s28, s29, s16
	global_load_lds_dwordx4 v[158:159], off
	v_lshl_add_u64 v[158:159], s[26:27], 0, v[192:193]
	s_mov_b32 m0, s28
	s_nop 0
	global_load_lds_dwordx4 v[158:159], off
	v_lshl_add_u64 v[158:159], s[26:27], 0, v[144:145]
	s_add_i32 m0, s28, 0x2000
	s_nop 0
	global_load_lds_dwordx4 v[158:159], off
	v_lshl_add_u64 v[158:159], v[196:197], 0, s[68:69]
	s_mov_b32 m0, s21
	s_nop 0
	global_load_lds_dwordx4 v[158:159], off
	v_lshl_add_u64 v[158:159], v[200:201], 0, s[68:69]
	s_mov_b32 m0, s91
	s_nop 0
	global_load_lds_dwordx4 v[158:159], off
	s_waitcnt vmcnt(8)
	s_waitcnt lgkmcnt(0)
	s_barrier
	s_setprio 1
	s_waitcnt lgkmcnt(0)
	v_mfma_f32_16x16x32_bf16 v[64:67], v[60:63], v[176:179], v[64:67]
	v_mfma_f32_16x16x32_bf16 v[56:59], v[72:75], v[176:179], v[56:59]
	v_mfma_f32_16x16x32_bf16 v[44:47], v[60:63], v[184:187], v[44:47]
	v_mfma_f32_16x16x32_bf16 v[40:43], v[72:75], v[184:187], v[40:43]
	v_mfma_f32_16x16x32_bf16 v[28:31], v[60:63], v[210:213], v[28:31]
	v_mfma_f32_16x16x32_bf16 v[24:27], v[72:75], v[210:213], v[24:27]
	v_mfma_f32_16x16x32_bf16 v[12:15], v[60:63], v[218:221], v[12:15]
	v_mfma_f32_16x16x32_bf16 v[8:11], v[72:75], v[218:221], v[8:11]
	v_mfma_f32_16x16x32_bf16 v[64:67], v[68:71], v[180:183], v[64:67]
	v_mfma_f32_16x16x32_bf16 v[56:59], v[76:79], v[180:183], v[56:59]
	v_mfma_f32_16x16x32_bf16 v[44:47], v[68:71], v[188:191], v[44:47]
	v_mfma_f32_16x16x32_bf16 v[40:43], v[76:79], v[188:191], v[40:43]
	v_mfma_f32_16x16x32_bf16 v[28:31], v[68:71], v[214:217], v[28:31]
	v_mfma_f32_16x16x32_bf16 v[24:27], v[76:79], v[214:217], v[24:27]
	v_mfma_f32_16x16x32_bf16 v[12:15], v[68:71], v[222:225], v[12:15]
	v_mfma_f32_16x16x32_bf16 v[8:11], v[76:79], v[222:225], v[8:11]
	s_setprio 0
	s_setprio 1
	v_mfma_f32_16x16x32_bf16 v[52:55], v[154:157], v[176:179], v[52:55]
	v_mfma_f32_16x16x32_bf16 v[48:51], v[168:171], v[176:179], v[48:51]
	v_mfma_f32_16x16x32_bf16 v[36:39], v[154:157], v[184:187], v[36:39]
	v_mfma_f32_16x16x32_bf16 v[32:35], v[168:171], v[184:187], v[32:35]
	v_mfma_f32_16x16x32_bf16 v[20:23], v[154:157], v[210:213], v[20:23]
	v_mfma_f32_16x16x32_bf16 v[16:19], v[168:171], v[210:213], v[16:19]
	v_mfma_f32_16x16x32_bf16 v[4:7], v[154:157], v[218:221], v[4:7]
	v_mfma_f32_16x16x32_bf16 v[0:3], v[168:171], v[218:221], v[0:3]
	v_mfma_f32_16x16x32_bf16 v[52:55], v[164:167], v[180:183], v[52:55]
	v_mfma_f32_16x16x32_bf16 v[48:51], v[172:175], v[180:183], v[48:51]
	v_mfma_f32_16x16x32_bf16 v[36:39], v[164:167], v[188:191], v[36:39]
	v_mfma_f32_16x16x32_bf16 v[32:35], v[172:175], v[188:191], v[32:35]
	v_mfma_f32_16x16x32_bf16 v[20:23], v[164:167], v[214:217], v[20:23]
	v_mfma_f32_16x16x32_bf16 v[16:19], v[172:175], v[214:217], v[16:19]
	v_mfma_f32_16x16x32_bf16 v[4:7], v[164:167], v[222:225], v[4:7]
	v_mfma_f32_16x16x32_bf16 v[0:3], v[172:175], v[222:225], v[0:3]
	s_setprio 0
	s_add_i32 s25, s25, 2
	s_add_u32 s44, s44, 0x100
	s_addc_u32 s45, s45, 0
	s_add_u32 vcc_hi, vcc_hi, 0x100
	s_addc_u32 s24, s24, 0
	s_cmp_gt_u32 s25, 29
	s_barrier
	s_cbranch_scc0 .LBB0_156
	s_and_b64 vcc, exec, s[58:59]
	s_cbranch_vccz .LBB0_159
	s_barrier

; #define PG8_STAGE(bufoff, gbase, voff) do { _Pragma("unroll") for (int _i = 0; _i < 2; ++_i) _Pragma("unroll") for (int _r = 0; _r < PG8_NREP; ++_r) \
;         __builtin_amdgcn_global_load_lds((const unsigned*)((const char*)(gbase) + (voff)[_i]), (PG8_LAS unsigned*)(lds + (bufoff) + ldsw + _i * 8192), 16, 0, 0); } while (0)
; #define PG8_LDA(dst, b, h) do { _Pragma("unroll") for (int m = 0; m < 4; ++m) _Pragma("unroll") for (int k = 0; k < 2; ++k) { dst[m][k] = *(const PG8_LAS bf16x8*)(lds + PG8_SA(b, h) + aoff + m * 2048 + k * 1024); PG8_DUP((unsigned)(uintptr_t)(lds + PG8_SA(b, h) + aoff + m * 2048 + k * 1024)); } } while (0)
; #define PG8_LDB(dst, b, h) do { _Pragma("unroll") for (int n = 0; n < 2; ++n) _Pragma("unroll") for (int k = 0; k < 2; ++k) { dst[n][k] = *(const PG8_LAS bf16x8*)(lds + PG8_SB(b, h) + boff + n * 2048 + k * 1024); PG8_DUP((unsigned)(uintptr_t)(lds + PG8_SB(b, h) + boff + n * 2048 + k * 1024)); } } while (0)
; #define PG8_MMA(ai, bj, At, Bt) do { __builtin_amdgcn_s_setprio(1); _Pragma("unroll") for (int m = 0; m < 4; ++m) _Pragma("unroll") for (int n = 0; n < 2; ++n) _Pragma("unroll") for (int k = 0; k < 2; ++k) \
;         acc[ai][bj][m][n] = __builtin_amdgcn_mfma_f32_16x16x32_bf16(Bt[n][k], At[m][k], acc[ai][bj][m][n], 0, 0, 0); __builtin_amdgcn_s_setprio(0); } while (0)
; template <class Epi, class Sched, bool ALIGN_EPI = false, bool SP2 = false>
; __device__ __forceinline__ void gemm_phase(PG8_LAS unsigned char* lds, const Gemm g, const Sched& S, const Epi& E) {
;     ...
;             const bool last = (t == nt - 2);
;             const char* a1 = cA + (size_t)(t + 1) * kstep;
;             const char* a2 = last ? nA : cA + (size_t)(t + 2) * kstep; const char* b2 = last ? nB : cB + (size_t)(t + 2) * kstep;
;             const char* a3 = a2 + kstep; const char* b3 = b2 + kstep;
;             if (last && has_next) S.a_ready(nxt);
;             if constexpr (SP2) {
;     ...
;             if (Epi::PERM && sizeof(Epi) && TEST_DRAIN) PG8_WAIT_V(0);
;     ...
;             PG8_LDB(B0, 0, 0); PG8_LDB(B1, 0, 1); PG8_SCHED; PG8_LDA(At, 0, 0); PG8_STAGE(PG8_SA(1, 1), a1 + hstepA, voffA);
;             PG8_WAIT_V(8); PG8_WAIT_L(0); PG8_BAR; PG8_MMA(0, 0, At, B0); PG8_MMA(0, 1, At, B1); PG8_BAR; PG8_SCHED;
;             PG8_LDA(At, 0, 1); PG8_STAGE(PG8_SB(0, 0), b2, voffB); PG8_STAGE(PG8_SB(0, 1), b2 + hstepB, voffB); PG8_STAGE(PG8_SA(0, 0), a2, voffA);
.LBB0_592:
	s_add_u32 s26, s54, 0xfffc0080
	s_addc_u32 s27, s55, -1
	s_add_i32 s28, 0, 0x10000
	s_cmp_eq_u32 s25, 12
	s_cselect_b32 s63, s47, s27
	s_cselect_b32 s62, s92, s26
	s_cselect_b32 s59, s45, s24
	s_cselect_b32 s58, s93, s94
	s_add_i32 s29, 0, 0x14000
	v_add_u32_e32 v154, s28, v143
	v_add_u32_e32 v170, s29, v143
	ds_read_b128 v[138:141], v154
	ds_read_b128 v[146:149], v154 offset:1024
	ds_read_b128 v[150:153], v154 offset:2048
	ds_read_b128 v[154:157], v154 offset:3072
	ds_read_b128 v[158:161], v170
	ds_read_b128 v[162:165], v170 offset:1024
	ds_read_b128 v[166:169], v170 offset:2048
	ds_read_b128 v[170:173], v170 offset:3072
	v_lshl_add_u64 v[190:191], s[54:55], 0, v[134:135]
	s_add_i32 m0, s17, 0xc000
	ds_read_b128 v[174:177], v145
	ds_read_b128 v[178:181], v145 offset:1024
	ds_read_b128 v[182:185], v145 offset:2048
	ds_read_b128 v[186:189], v145 offset:3072
	ds_read_b128 v[210:213], v145 offset:4096
	ds_read_b128 v[214:217], v145 offset:5120
	ds_read_b128 v[218:221], v145 offset:6144
	ds_read_b128 v[222:225], v145 offset:7168
	global_load_lds_dwordx4 v[190:191], off
	v_lshl_add_u64 v[190:191], s[54:55], 0, v[136:137]
	s_add_i32 m0, s17, 0xe000
	s_nop 0
	global_load_lds_dwordx4 v[190:191], off
	s_waitcnt vmcnt(8)
	s_waitcnt lgkmcnt(0)
	s_barrier
	s_setprio 1
	s_waitcnt lgkmcnt(0)
	v_mfma_f32_16x16x32_bf16 v[124:127], v[138:141], v[174:177], v[124:127]
	v_mfma_f32_16x16x32_bf16 v[120:123], v[150:153], v[174:177], v[120:123]
	v_mfma_f32_16x16x32_bf16 v[112:115], v[138:141], v[182:185], v[112:115]
	v_mfma_f32_16x16x32_bf16 v[104:107], v[150:153], v[182:185], v[104:107]
	v_mfma_f32_16x16x32_bf16 v[96:99], v[138:141], v[210:213], v[96:99]
	v_mfma_f32_16x16x32_bf16 v[88:91], v[150:153], v[210:213], v[88:91]
	v_mfma_f32_16x16x32_bf16 v[80:83], v[138:141], v[218:221], v[80:83]
	v_mfma_f32_16x16x32_bf16 v[72:75], v[150:153], v[218:221], v[72:75]
	v_mfma_f32_16x16x32_bf16 v[124:127], v[146:149], v[178:181], v[124:127]
	v_mfma_f32_16x16x32_bf16 v[120:123], v[154:157], v[178:181], v[120:123]
	v_mfma_f32_16x16x32_bf16 v[112:115], v[146:149], v[186:189], v[112:115]
	v_mfma_f32_16x16x32_bf16 v[104:107], v[154:157], v[186:189], v[104:107]
	v_mfma_f32_16x16x32_bf16 v[96:99], v[146:149], v[214:217], v[96:99]
	v_mfma_f32_16x16x32_bf16 v[88:91], v[154:157], v[214:217], v[88:91]
	v_mfma_f32_16x16x32_bf16 v[80:83], v[146:149], v[222:225], v[80:83]
	v_mfma_f32_16x16x32_bf16 v[72:75], v[154:157], v[222:225], v[72:75]
	s_setprio 0
	s_setprio 1
	v_mfma_f32_16x16x32_bf16 v[116:119], v[158:161], v[174:177], v[116:119]
	v_mfma_f32_16x16x32_bf16 v[108:111], v[166:169], v[174:177], v[108:111]
	v_mfma_f32_16x16x32_bf16 v[100:103], v[158:161], v[182:185], v[100:103]
	v_mfma_f32_16x16x32_bf16 v[92:95], v[166:169], v[182:185], v[92:95]
	v_mfma_f32_16x16x32_bf16 v[84:87], v[158:161], v[210:213], v[84:87]
	v_mfma_f32_16x16x32_bf16 v[76:79], v[166:169], v[210:213], v[76:79]
	v_mfma_f32_16x16x32_bf16 v[68:71], v[158:161], v[218:221], v[68:71]
	v_mfma_f32_16x16x32_bf16 v[64:67], v[166:169], v[218:221], v[64:67]
	v_mfma_f32_16x16x32_bf16 v[116:119], v[162:165], v[178:181], v[116:119]
	v_mfma_f32_16x16x32_bf16 v[108:111], v[170:173], v[178:181], v[108:111]
	v_mfma_f32_16x16x32_bf16 v[100:103], v[162:165], v[186:189], v[100:103]
	v_mfma_f32_16x16x32_bf16 v[92:95], v[170:173], v[186:189], v[92:95]
	v_mfma_f32_16x16x32_bf16 v[84:87], v[162:165], v[214:217], v[84:87]
	v_mfma_f32_16x16x32_bf16 v[76:79], v[170:173], v[214:217], v[76:79]
	v_mfma_f32_16x16x32_bf16 v[68:71], v[162:165], v[222:225], v[68:71]
	v_mfma_f32_16x16x32_bf16 v[64:67], v[170:173], v[222:225], v[64:67]
	s_setprio 0
	s_barrier
	s_add_i32 s26, s28, s16
	v_lshl_add_u64 v[190:191], s[58:59], 0, v[192:193]
	s_mov_b32 m0, s26
	ds_read_b128 v[174:177], v145 offset:16384
	ds_read_b128 v[178:181], v145 offset:17408
	ds_read_b128 v[182:185], v145 offset:18432
	ds_read_b128 v[186:189], v145 offset:19456
	ds_read_b128 v[210:213], v145 offset:20480
	ds_read_b128 v[214:217], v145 offset:21504
	ds_read_b128 v[218:221], v145 offset:22528
	ds_read_b128 v[222:225], v145 offset:23552
	global_load_lds_dwordx4 v[190:191], off
	s_add_i32 m0, s26, 0x2000
	s_add_u32 s26, s58, 0x40000
	v_lshl_add_u64 v[194:195], s[58:59], 0, v[128:129]
	s_addc_u32 s27, s59, 0
	s_add_i32 s28, s29, s16
	global_load_lds_dwordx4 v[194:195], off
	v_lshl_add_u64 v[196:197], s[26:27], 0, v[192:193]
	s_mov_b32 m0, s28
	v_lshl_add_u64 v[200:201], s[62:63], 0, v[130:131]
	global_load_lds_dwordx4 v[196:197], off
	v_lshl_add_u64 v[196:197], s[26:27], 0, v[128:129]
	s_add_i32 m0, s28, 0x2000
	s_nop 0
	global_load_lds_dwordx4 v[196:197], off
	v_lshl_add_u64 v[196:197], s[62:63], 0, v[132:133]
	s_mov_b32 m0, s17
	s_nop 0
	global_load_lds_dwordx4 v[196:197], off
	s_mov_b32 m0, s18
	s_nop 0
	global_load_lds_dwordx4 v[200:201], off
	s_waitcnt vmcnt(8)
	s_waitcnt lgkmcnt(0)
	s_barrier
; #define PG8_STAGE(bufoff, gbase, voff) do { _Pragma("unroll") for (int _i = 0; _i < 2; ++_i) _Pragma("unroll") for (int _r = 0; _r < PG8_NREP; ++_r) \
;         __builtin_amdgcn_global_load_lds((const unsigned*)((const char*)(gbase) + (voff)[_i]), (PG8_LAS unsigned*)(lds + (bufoff) + ldsw + _i * 8192), 16, 0, 0); } while (0)
; #define PG8_LDA(dst, b, h) do { _Pragma("unroll") for (int m = 0; m < 4; ++m) _Pragma("unroll") for (int k = 0; k < 2; ++k) { dst[m][k] = *(const PG8_LAS bf16x8*)(lds + PG8_SA(b, h) + aoff + m * 2048 + k * 1024); PG8_DUP((unsigned)(uintptr_t)(lds + PG8_SA(b, h) + aoff + m * 2048 + k * 1024)); } } while (0)
; #define PG8_LDB(dst, b, h) do { _Pragma("unroll") for (int n = 0; n < 2; ++n) _Pragma("unroll") for (int k = 0; k < 2; ++k) { dst[n][k] = *(const PG8_LAS bf16x8*)(lds + PG8_SB(b, h) + boff + n * 2048 + k * 1024); PG8_DUP((unsigned)(uintptr_t)(lds + PG8_SB(b, h) + boff + n * 2048 + k * 1024)); } } while (0)
; #define PG8_MMA(ai, bj, At, Bt) do { __builtin_amdgcn_s_setprio(1); _Pragma("unroll") for (int m = 0; m < 4; ++m) _Pragma("unroll") for (int n = 0; n < 2; ++n) _Pragma("unroll") for (int k = 0; k < 2; ++k) \
;         acc[ai][bj][m][n] = __builtin_amdgcn_mfma_f32_16x16x32_bf16(Bt[n][k], At[m][k], acc[ai][bj][m][n], 0, 0, 0); __builtin_amdgcn_s_setprio(0); } while (0)
; #define PG8_WAIT_V(n) do { if ((n) == 0) asm volatile("s_waitcnt vmcnt(0)" ::: "memory"); else if ((n) == 2) asm volatile("s_waitcnt vmcnt(4)" ::: "memory"); else if ((n) == 4) asm volatile("s_waitcnt vmcnt(8)" ::: "memory"); \
;     else if ((n) == 6) asm volatile("s_waitcnt vmcnt(12)" ::: "memory"); else asm volatile("s_waitcnt vmcnt(16)" ::: "memory"); } while (0)
; #define PG8_WAIT_V(n) asm volatile("s_waitcnt vmcnt(" #n ")" ::: "memory")
; #define PG8_BAR __builtin_amdgcn_s_barrier()
; template <class Epi, class Sched, bool ALIGN_EPI = false, bool SP2 = false>
; __device__ __forceinline__ void gemm_phase(PG8_LAS unsigned char* lds, const Gemm g, const Sched& S, const Epi& E) {
;     ...
;             PG8_WAIT_V(8); PG8_WAIT_L(0); PG8_BAR; PG8_MMA(1, 0, At, B0); PG8_MMA(1, 1, At, B1); PG8_BAR; PG8_SCHED;
;             PG8_LDB(B0, 1, 0); PG8_LDB(B1, 1, 1); PG8_SCHED; PG8_LDA(At, 1, 0); PG8_STAGE(PG8_SA(0, 1), a2 + hstepA, voffA);
;             PG8_WAIT_V(8); PG8_WAIT_L(0); PG8_BAR; PG8_MMA(0, 0, At, B0); PG8_MMA(0, 1, At, B1); PG8_BAR; PG8_SCHED;
	s_setprio 1
	s_waitcnt lgkmcnt(0)
	v_mfma_f32_16x16x32_bf16 v[60:63], v[138:141], v[174:177], v[60:63]
	v_mfma_f32_16x16x32_bf16 v[56:59], v[150:153], v[174:177], v[56:59]
	v_mfma_f32_16x16x32_bf16 v[48:51], v[138:141], v[182:185], v[48:51]
	v_mfma_f32_16x16x32_bf16 v[40:43], v[150:153], v[182:185], v[40:43]
	v_mfma_f32_16x16x32_bf16 v[32:35], v[138:141], v[210:213], v[32:35]
	v_mfma_f32_16x16x32_bf16 v[24:27], v[150:153], v[210:213], v[24:27]
	v_mfma_f32_16x16x32_bf16 v[16:19], v[138:141], v[218:221], v[16:19]
	v_mfma_f32_16x16x32_bf16 v[8:11], v[150:153], v[218:221], v[8:11]
	v_mfma_f32_16x16x32_bf16 v[60:63], v[146:149], v[178:181], v[60:63]
	v_mfma_f32_16x16x32_bf16 v[56:59], v[154:157], v[178:181], v[56:59]
	v_mfma_f32_16x16x32_bf16 v[48:51], v[146:149], v[186:189], v[48:51]
	v_mfma_f32_16x16x32_bf16 v[40:43], v[154:157], v[186:189], v[40:43]
	v_mfma_f32_16x16x32_bf16 v[32:35], v[146:149], v[214:217], v[32:35]
	v_mfma_f32_16x16x32_bf16 v[24:27], v[154:157], v[214:217], v[24:27]
	v_mfma_f32_16x16x32_bf16 v[16:19], v[146:149], v[222:225], v[16:19]
	v_mfma_f32_16x16x32_bf16 v[8:11], v[154:157], v[222:225], v[8:11]
	s_setprio 0
	s_setprio 1
	v_mfma_f32_16x16x32_bf16 v[52:55], v[158:161], v[174:177], v[52:55]
	v_mfma_f32_16x16x32_bf16 v[44:47], v[166:169], v[174:177], v[44:47]
	v_mfma_f32_16x16x32_bf16 v[36:39], v[158:161], v[182:185], v[36:39]
	v_mfma_f32_16x16x32_bf16 v[28:31], v[166:169], v[182:185], v[28:31]
	v_mfma_f32_16x16x32_bf16 v[20:23], v[158:161], v[210:213], v[20:23]
	v_mfma_f32_16x16x32_bf16 v[12:15], v[166:169], v[210:213], v[12:15]
	v_mfma_f32_16x16x32_bf16 v[4:7], v[158:161], v[218:221], v[4:7]
	v_mfma_f32_16x16x32_bf16 v[0:3], v[166:169], v[218:221], v[0:3]
	v_mfma_f32_16x16x32_bf16 v[52:55], v[162:165], v[178:181], v[52:55]
	v_mfma_f32_16x16x32_bf16 v[44:47], v[170:173], v[178:181], v[44:47]
	v_mfma_f32_16x16x32_bf16 v[36:39], v[162:165], v[186:189], v[36:39]
	v_mfma_f32_16x16x32_bf16 v[28:31], v[170:173], v[186:189], v[28:31]
	v_mfma_f32_16x16x32_bf16 v[20:23], v[162:165], v[214:217], v[20:23]
	v_mfma_f32_16x16x32_bf16 v[12:15], v[170:173], v[214:217], v[12:15]
	v_mfma_f32_16x16x32_bf16 v[4:7], v[162:165], v[222:225], v[4:7]
	v_mfma_f32_16x16x32_bf16 v[0:3], v[170:173], v[222:225], v[0:3]
	s_setprio 0
	s_barrier
	s_add_i32 s28, 0, 0x18000
	s_add_i32 s29, 0, 0x1c000
	v_add_u32_e32 v154, s28, v143
	v_add_u32_e32 v170, s29, v143
	ds_read_b128 v[138:141], v154
	ds_read_b128 v[146:149], v154 offset:1024
	ds_read_b128 v[150:153], v154 offset:2048
	ds_read_b128 v[154:157], v154 offset:3072
	ds_read_b128 v[158:161], v170
	ds_read_b128 v[162:165], v170 offset:1024
	ds_read_b128 v[166:169], v170 offset:2048
	ds_read_b128 v[170:173], v170 offset:3072
	s_add_u32 s26, s62, 0x40000
	s_addc_u32 s27, s63, 0
	s_mov_b32 m0, s19
	v_lshl_add_u64 v[226:227], s[26:27], 0, v[132:133]
	ds_read_b128 v[174:177], v145 offset:32768
	ds_read_b128 v[178:181], v145 offset:33792
	ds_read_b128 v[182:185], v145 offset:34816
	ds_read_b128 v[186:189], v145 offset:35840
	ds_read_b128 v[210:213], v145 offset:36864
	ds_read_b128 v[214:217], v145 offset:37888
	ds_read_b128 v[218:221], v145 offset:38912
	ds_read_b128 v[222:225], v145 offset:39936
	global_load_lds_dwordx4 v[226:227], off
	v_lshl_add_u64 v[226:227], s[26:27], 0, v[130:131]
	s_mov_b32 m0, s20
	s_nop 0
	global_load_lds_dwordx4 v[226:227], off
	s_waitcnt vmcnt(8)
	s_waitcnt lgkmcnt(0)
	s_barrier
	s_setprio 1
	s_waitcnt lgkmcnt(0)
	v_mfma_f32_16x16x32_bf16 v[124:127], v[138:141], v[174:177], v[124:127]
	v_mfma_f32_16x16x32_bf16 v[120:123], v[150:153], v[174:177], v[120:123]
	v_mfma_f32_16x16x32_bf16 v[112:115], v[138:141], v[182:185], v[112:115]
	v_mfma_f32_16x16x32_bf16 v[104:107], v[150:153], v[182:185], v[104:107]
	v_mfma_f32_16x16x32_bf16 v[96:99], v[138:141], v[210:213], v[96:99]
	v_mfma_f32_16x16x32_bf16 v[88:91], v[150:153], v[210:213], v[88:91]
	v_mfma_f32_16x16x32_bf16 v[80:83], v[138:141], v[218:221], v[80:83]
	v_mfma_f32_16x16x32_bf16 v[72:75], v[150:153], v[218:221], v[72:75]
	v_mfma_f32_16x16x32_bf16 v[124:127], v[146:149], v[178:181], v[124:127]
	v_mfma_f32_16x16x32_bf16 v[120:123], v[154:157], v[178:181], v[120:123]
	v_mfma_f32_16x16x32_bf16 v[112:115], v[146:149], v[186:189], v[112:115]
	v_mfma_f32_16x16x32_bf16 v[104:107], v[154:157], v[186:189], v[104:107]
	v_mfma_f32_16x16x32_bf16 v[96:99], v[146:149], v[214:217], v[96:99]
	v_mfma_f32_16x16x32_bf16 v[88:91], v[154:157], v[214:217], v[88:91]
	v_mfma_f32_16x16x32_bf16 v[80:83], v[146:149], v[222:225], v[80:83]
	v_mfma_f32_16x16x32_bf16 v[72:75], v[154:157], v[222:225], v[72:75]
	s_setprio 0
	s_setprio 1
	v_mfma_f32_16x16x32_bf16 v[116:119], v[158:161], v[174:177], v[116:119]
	v_mfma_f32_16x16x32_bf16 v[108:111], v[166:169], v[174:177], v[108:111]
	v_mfma_f32_16x16x32_bf16 v[100:103], v[158:161], v[182:185], v[100:103]
	v_mfma_f32_16x16x32_bf16 v[92:95], v[166:169], v[182:185], v[92:95]
	v_mfma_f32_16x16x32_bf16 v[84:87], v[158:161], v[210:213], v[84:87]
	v_mfma_f32_16x16x32_bf16 v[76:79], v[166:169], v[210:213], v[76:79]
	v_mfma_f32_16x16x32_bf16 v[68:71], v[158:161], v[218:221], v[68:71]
	v_mfma_f32_16x16x32_bf16 v[64:67], v[166:169], v[218:221], v[64:67]
	v_mfma_f32_16x16x32_bf16 v[116:119], v[162:165], v[178:181], v[116:119]
	v_mfma_f32_16x16x32_bf16 v[108:111], v[170:173], v[178:181], v[108:111]
	v_mfma_f32_16x16x32_bf16 v[100:103], v[162:165], v[186:189], v[100:103]
	v_mfma_f32_16x16x32_bf16 v[92:95], v[170:173], v[186:189], v[92:95]
	v_mfma_f32_16x16x32_bf16 v[84:87], v[162:165], v[214:217], v[84:87]
	v_mfma_f32_16x16x32_bf16 v[76:79], v[170:173], v[214:217], v[76:79]
	v_mfma_f32_16x16x32_bf16 v[68:71], v[162:165], v[222:225], v[68:71]
	v_mfma_f32_16x16x32_bf16 v[64:67], v[170:173], v[222:225], v[64:67]
	s_setprio 0
	s_barrier
; #define PG8_STAGE(bufoff, gbase, voff) do { _Pragma("unroll") for (int _i = 0; _i < 2; ++_i) _Pragma("unroll") for (int _r = 0; _r < PG8_NREP; ++_r) \
;         __builtin_amdgcn_global_load_lds((const unsigned*)((const char*)(gbase) + (voff)[_i]), (PG8_LAS unsigned*)(lds + (bufoff) + ldsw + _i * 8192), 16, 0, 0); } while (0)
; #define PG8_LDA(dst, b, h) do { _Pragma("unroll") for (int m = 0; m < 4; ++m) _Pragma("unroll") for (int k = 0; k < 2; ++k) { dst[m][k] = *(const PG8_LAS bf16x8*)(lds + PG8_SA(b, h) + aoff + m * 2048 + k * 1024); PG8_DUP((unsigned)(uintptr_t)(lds + PG8_SA(b, h) + aoff + m * 2048 + k * 1024)); } } while (0)
; #define PG8_MMA(ai, bj, At, Bt) do { __builtin_amdgcn_s_setprio(1); _Pragma("unroll") for (int m = 0; m < 4; ++m) _Pragma("unroll") for (int n = 0; n < 2; ++n) _Pragma("unroll") for (int k = 0; k < 2; ++k) \
;         acc[ai][bj][m][n] = __builtin_amdgcn_mfma_f32_16x16x32_bf16(Bt[n][k], At[m][k], acc[ai][bj][m][n], 0, 0, 0); __builtin_amdgcn_s_setprio(0); } while (0)
; #define PG8_WAIT_V(n) do { if ((n) == 0) asm volatile("s_waitcnt vmcnt(0)" ::: "memory"); else if ((n) == 2) asm volatile("s_waitcnt vmcnt(4)" ::: "memory"); else if ((n) == 4) asm volatile("s_waitcnt vmcnt(8)" ::: "memory"); \
;     else if ((n) == 6) asm volatile("s_waitcnt vmcnt(12)" ::: "memory"); else asm volatile("s_waitcnt vmcnt(16)" ::: "memory"); } while (0)
; #define PG8_WAIT_V(n) asm volatile("s_waitcnt vmcnt(" #n ")" ::: "memory")
; #define PG8_WAIT_L(n) asm volatile("s_waitcnt lgkmcnt(" #n ")" ::: "memory")
; #define PG8_BAR __builtin_amdgcn_s_barrier()
; #define PG8_SCHED __builtin_amdgcn_sched_barrier(0)
; template <class Epi, class Sched, bool ALIGN_EPI = false, bool SP2 = false>
; __device__ __forceinline__ void gemm_phase(PG8_LAS unsigned char* lds, const Gemm g, const Sched& S, const Epi& E) {
;     ...
;             PG8_LDA(At, 1, 1); PG8_STAGE(PG8_SB(1, 0), b3, voffB); PG8_STAGE(PG8_SB(1, 1), b3 + hstepB, voffB); PG8_STAGE(PG8_SA(1, 0), a3, voffA);
;             PG8_WAIT_V(8); PG8_WAIT_L(0); PG8_BAR; PG8_MMA(1, 0, At, B0); PG8_MMA(1, 1, At, B1); PG8_BAR; PG8_SCHED;
;     ...
;         if constexpr (ALIGN_EPI) { if (wr == 0) PG8_BAR; }
	s_add_i32 s26, s28, s16
	v_lshl_add_u64 v[190:191], v[190:191], 0, s[68:69]
	s_mov_b32 m0, s26
	ds_read_b128 v[174:177], v145 offset:49152
	ds_read_b128 v[178:181], v145 offset:50176
	ds_read_b128 v[182:185], v145 offset:51200
	ds_read_b128 v[186:189], v145 offset:52224
	ds_read_b128 v[210:213], v145 offset:53248
	ds_read_b128 v[214:217], v145 offset:54272
	ds_read_b128 v[218:221], v145 offset:55296
	ds_read_b128 v[222:225], v145 offset:56320
	global_load_lds_dwordx4 v[190:191], off
	s_add_i32 m0, s26, 0x2000
	s_add_u32 s26, s58, 0x40080
	v_lshl_add_u64 v[190:191], v[194:195], 0, s[68:69]
	s_addc_u32 s27, s59, 0
	s_add_i32 s28, s29, s16
	global_load_lds_dwordx4 v[190:191], off
	v_lshl_add_u64 v[190:191], s[26:27], 0, v[192:193]
	s_mov_b32 m0, s28
	s_nop 0
	global_load_lds_dwordx4 v[190:191], off
	v_lshl_add_u64 v[190:191], s[26:27], 0, v[128:129]
	s_add_i32 m0, s28, 0x2000
	s_nop 0
	global_load_lds_dwordx4 v[190:191], off
	v_lshl_add_u64 v[190:191], v[196:197], 0, s[68:69]
	s_mov_b32 m0, s21
	s_nop 0
	global_load_lds_dwordx4 v[190:191], off
	v_lshl_add_u64 v[190:191], v[200:201], 0, s[68:69]
	s_mov_b32 m0, s22
	s_nop 0
	global_load_lds_dwordx4 v[190:191], off
	s_waitcnt vmcnt(8)
	s_waitcnt lgkmcnt(0)
	s_barrier
	s_setprio 1
	s_waitcnt lgkmcnt(0)
	v_mfma_f32_16x16x32_bf16 v[60:63], v[138:141], v[174:177], v[60:63]
	v_mfma_f32_16x16x32_bf16 v[56:59], v[150:153], v[174:177], v[56:59]
	v_mfma_f32_16x16x32_bf16 v[48:51], v[138:141], v[182:185], v[48:51]
	v_mfma_f32_16x16x32_bf16 v[40:43], v[150:153], v[182:185], v[40:43]
	v_mfma_f32_16x16x32_bf16 v[32:35], v[138:141], v[210:213], v[32:35]
	v_mfma_f32_16x16x32_bf16 v[24:27], v[150:153], v[210:213], v[24:27]
	v_mfma_f32_16x16x32_bf16 v[16:19], v[138:141], v[218:221], v[16:19]
	v_mfma_f32_16x16x32_bf16 v[8:11], v[150:153], v[218:221], v[8:11]
	v_mfma_f32_16x16x32_bf16 v[60:63], v[146:149], v[178:181], v[60:63]
	v_mfma_f32_16x16x32_bf16 v[56:59], v[154:157], v[178:181], v[56:59]
	v_mfma_f32_16x16x32_bf16 v[48:51], v[146:149], v[186:189], v[48:51]
	v_mfma_f32_16x16x32_bf16 v[40:43], v[154:157], v[186:189], v[40:43]
	v_mfma_f32_16x16x32_bf16 v[32:35], v[146:149], v[214:217], v[32:35]
	v_mfma_f32_16x16x32_bf16 v[24:27], v[154:157], v[214:217], v[24:27]
	v_mfma_f32_16x16x32_bf16 v[16:19], v[146:149], v[222:225], v[16:19]
	v_mfma_f32_16x16x32_bf16 v[8:11], v[154:157], v[222:225], v[8:11]
	s_setprio 0
	s_setprio 1
	v_mfma_f32_16x16x32_bf16 v[52:55], v[158:161], v[174:177], v[52:55]
	v_mfma_f32_16x16x32_bf16 v[44:47], v[166:169], v[174:177], v[44:47]
	v_mfma_f32_16x16x32_bf16 v[36:39], v[158:161], v[182:185], v[36:39]
	v_mfma_f32_16x16x32_bf16 v[28:31], v[166:169], v[182:185], v[28:31]
	v_mfma_f32_16x16x32_bf16 v[20:23], v[158:161], v[210:213], v[20:23]
	v_mfma_f32_16x16x32_bf16 v[12:15], v[166:169], v[210:213], v[12:15]
	v_mfma_f32_16x16x32_bf16 v[4:7], v[158:161], v[218:221], v[4:7]
	v_mfma_f32_16x16x32_bf16 v[0:3], v[166:169], v[218:221], v[0:3]
	v_mfma_f32_16x16x32_bf16 v[52:55], v[162:165], v[178:181], v[52:55]
	v_mfma_f32_16x16x32_bf16 v[44:47], v[170:173], v[178:181], v[44:47]
	v_mfma_f32_16x16x32_bf16 v[36:39], v[162:165], v[186:189], v[36:39]
	v_mfma_f32_16x16x32_bf16 v[28:31], v[170:173], v[186:189], v[28:31]
	v_mfma_f32_16x16x32_bf16 v[20:23], v[162:165], v[214:217], v[20:23]
	v_mfma_f32_16x16x32_bf16 v[12:15], v[170:173], v[214:217], v[12:15]
	v_mfma_f32_16x16x32_bf16 v[4:7], v[162:165], v[222:225], v[4:7]
	v_mfma_f32_16x16x32_bf16 v[0:3], v[170:173], v[222:225], v[0:3]
	s_setprio 0
	s_add_i32 s25, s25, 2
	s_add_u32 s54, s54, 0x100
	s_addc_u32 s55, s55, 0
	s_add_u32 s94, s94, 0x100
	s_addc_u32 s24, s24, 0
	s_cmp_gt_u32 s25, 13
	s_barrier
	s_cbranch_scc0 .LBB0_592
	s_and_b64 vcc, exec, s[40:41]
	s_cbranch_vccz .LBB0_595
	s_barrier

; #define PG8_STAGE(bufoff, gbase, voff) do { _Pragma("unroll") for (int _i = 0; _i < 2; ++_i) _Pragma("unroll") for (int _r = 0; _r < PG8_NREP; ++_r) \
;         __builtin_amdgcn_global_load_lds((const unsigned*)((const char*)(gbase) + (voff)[_i]), (PG8_LAS unsigned*)(lds + (bufoff) + ldsw + _i * 8192), 16, 0, 0); } while (0)
; #define PG8_LDA(dst, b, h) do { _Pragma("unroll") for (int m = 0; m < 4; ++m) _Pragma("unroll") for (int k = 0; k < 2; ++k) { dst[m][k] = *(const PG8_LAS bf16x8*)(lds + PG8_SA(b, h) + aoff + m * 2048 + k * 1024); PG8_DUP((unsigned)(uintptr_t)(lds + PG8_SA(b, h) + aoff + m * 2048 + k * 1024)); } } while (0)
; #define PG8_LDB(dst, b, h) do { _Pragma("unroll") for (int n = 0; n < 2; ++n) _Pragma("unroll") for (int k = 0; k < 2; ++k) { dst[n][k] = *(const PG8_LAS bf16x8*)(lds + PG8_SB(b, h) + boff + n * 2048 + k * 1024); PG8_DUP((unsigned)(uintptr_t)(lds + PG8_SB(b, h) + boff + n * 2048 + k * 1024)); } } while (0)
; #define PG8_MMA(ai, bj, At, Bt) do { __builtin_amdgcn_s_setprio(1); _Pragma("unroll") for (int m = 0; m < 4; ++m) _Pragma("unroll") for (int n = 0; n < 2; ++n) _Pragma("unroll") for (int k = 0; k < 2; ++k) \
;         acc[ai][bj][m][n] = __builtin_amdgcn_mfma_f32_16x16x32_bf16(Bt[n][k], At[m][k], acc[ai][bj][m][n], 0, 0, 0); __builtin_amdgcn_s_setprio(0); } while (0)
; template <class Epi, class Sched, bool ALIGN_EPI = false, bool SP2 = false>
; __device__ __forceinline__ void gemm_phase(PG8_LAS unsigned char* lds, const Gemm g, const Sched& S, const Epi& E) {
;     ...
;             const bool last = (t == nt - 2);
;             const char* a1 = cA + (size_t)(t + 1) * kstep;
;             const char* a2 = last ? nA : cA + (size_t)(t + 2) * kstep; const char* b2 = last ? nB : cB + (size_t)(t + 2) * kstep;
;             const char* a3 = a2 + kstep; const char* b3 = b2 + kstep;
;             if (last && has_next) S.a_ready(nxt);
;             if constexpr (SP2) {
;     ...
;             if (Epi::PERM && sizeof(Epi) && TEST_DRAIN) PG8_WAIT_V(0);
;     ...
;             PG8_LDB(B0, 0, 0); PG8_LDB(B1, 0, 1); PG8_SCHED; PG8_LDA(At, 0, 0); PG8_STAGE(PG8_SA(1, 1), a1 + hstepA, voffA);
;             PG8_WAIT_V(8); PG8_WAIT_L(0); PG8_BAR; PG8_MMA(0, 0, At, B0); PG8_MMA(0, 1, At, B1); PG8_BAR; PG8_SCHED;
;             PG8_LDA(At, 0, 1); PG8_STAGE(PG8_SB(0, 0), b2, voffB); PG8_STAGE(PG8_SB(0, 1), b2 + hstepB, voffB); PG8_STAGE(PG8_SA(0, 0), a2, voffA);
.LBB0_612:
	s_add_u32 s26, s54, 0xfffc0080
	s_addc_u32 s27, s55, -1
	s_add_i32 s28, 0, 0x10000
	s_cmp_eq_u32 s25, 12
	s_cselect_b32 s63, s47, s27
	s_cselect_b32 s62, s92, s26
	s_cselect_b32 s59, s45, s24
	s_cselect_b32 s58, s93, s94
	s_add_i32 s29, 0, 0x14000
	v_add_u32_e32 v154, s28, v147
	v_add_u32_e32 v170, s29, v147
	ds_read_b128 v[138:141], v154
	ds_read_b128 v[142:145], v154 offset:1024
	ds_read_b128 v[150:153], v154 offset:2048
	ds_read_b128 v[154:157], v154 offset:3072
	ds_read_b128 v[158:161], v170
	ds_read_b128 v[162:165], v170 offset:1024
	ds_read_b128 v[166:169], v170 offset:2048
	ds_read_b128 v[170:173], v170 offset:3072
	v_lshl_add_u64 v[190:191], s[54:55], 0, v[134:135]
	s_add_i32 m0, s17, 0xc000
	ds_read_b128 v[174:177], v149
	ds_read_b128 v[178:181], v149 offset:1024
	ds_read_b128 v[182:185], v149 offset:2048
	ds_read_b128 v[186:189], v149 offset:3072
	ds_read_b128 v[210:213], v149 offset:4096
	ds_read_b128 v[214:217], v149 offset:5120
	ds_read_b128 v[218:221], v149 offset:6144
	ds_read_b128 v[222:225], v149 offset:7168
	global_load_lds_dwordx4 v[190:191], off
	v_lshl_add_u64 v[190:191], s[54:55], 0, v[136:137]
	s_add_i32 m0, s17, 0xe000
	s_nop 0
	global_load_lds_dwordx4 v[190:191], off
	s_waitcnt vmcnt(8)
	s_waitcnt lgkmcnt(0)
	s_barrier
	s_setprio 1
	s_waitcnt lgkmcnt(0)
	v_mfma_f32_16x16x32_bf16 v[124:127], v[138:141], v[174:177], v[124:127]
	v_mfma_f32_16x16x32_bf16 v[120:123], v[150:153], v[174:177], v[120:123]
	v_mfma_f32_16x16x32_bf16 v[108:111], v[138:141], v[182:185], v[108:111]
	v_mfma_f32_16x16x32_bf16 v[104:107], v[150:153], v[182:185], v[104:107]
	v_mfma_f32_16x16x32_bf16 v[92:95], v[138:141], v[210:213], v[92:95]
	v_mfma_f32_16x16x32_bf16 v[88:91], v[150:153], v[210:213], v[88:91]
	v_mfma_f32_16x16x32_bf16 v[76:79], v[138:141], v[218:221], v[76:79]
	v_mfma_f32_16x16x32_bf16 v[72:75], v[150:153], v[218:221], v[72:75]
	v_mfma_f32_16x16x32_bf16 v[124:127], v[142:145], v[178:181], v[124:127]
	v_mfma_f32_16x16x32_bf16 v[120:123], v[154:157], v[178:181], v[120:123]
	v_mfma_f32_16x16x32_bf16 v[108:111], v[142:145], v[186:189], v[108:111]
	v_mfma_f32_16x16x32_bf16 v[104:107], v[154:157], v[186:189], v[104:107]
	v_mfma_f32_16x16x32_bf16 v[92:95], v[142:145], v[214:217], v[92:95]
	v_mfma_f32_16x16x32_bf16 v[88:91], v[154:157], v[214:217], v[88:91]
	v_mfma_f32_16x16x32_bf16 v[76:79], v[142:145], v[222:225], v[76:79]
	v_mfma_f32_16x16x32_bf16 v[72:75], v[154:157], v[222:225], v[72:75]
	s_setprio 0
	s_setprio 1
	v_mfma_f32_16x16x32_bf16 v[116:119], v[158:161], v[174:177], v[116:119]
	v_mfma_f32_16x16x32_bf16 v[112:115], v[166:169], v[174:177], v[112:115]
	v_mfma_f32_16x16x32_bf16 v[100:103], v[158:161], v[182:185], v[100:103]
	v_mfma_f32_16x16x32_bf16 v[96:99], v[166:169], v[182:185], v[96:99]
	v_mfma_f32_16x16x32_bf16 v[84:87], v[158:161], v[210:213], v[84:87]
	v_mfma_f32_16x16x32_bf16 v[80:83], v[166:169], v[210:213], v[80:83]
	v_mfma_f32_16x16x32_bf16 v[68:71], v[158:161], v[218:221], v[68:71]
	v_mfma_f32_16x16x32_bf16 v[64:67], v[166:169], v[218:221], v[64:67]
	v_mfma_f32_16x16x32_bf16 v[116:119], v[162:165], v[178:181], v[116:119]
	v_mfma_f32_16x16x32_bf16 v[112:115], v[170:173], v[178:181], v[112:115]
	v_mfma_f32_16x16x32_bf16 v[100:103], v[162:165], v[186:189], v[100:103]
	v_mfma_f32_16x16x32_bf16 v[96:99], v[170:173], v[186:189], v[96:99]
	v_mfma_f32_16x16x32_bf16 v[84:87], v[162:165], v[214:217], v[84:87]
	v_mfma_f32_16x16x32_bf16 v[80:83], v[170:173], v[214:217], v[80:83]
	v_mfma_f32_16x16x32_bf16 v[68:71], v[162:165], v[222:225], v[68:71]
	v_mfma_f32_16x16x32_bf16 v[64:67], v[170:173], v[222:225], v[64:67]
	s_setprio 0
	s_barrier
	s_add_i32 s26, s28, s16
	v_lshl_add_u64 v[190:191], s[58:59], 0, v[192:193]
	s_mov_b32 m0, s26
	ds_read_b128 v[174:177], v149 offset:16384
	ds_read_b128 v[178:181], v149 offset:17408
	ds_read_b128 v[182:185], v149 offset:18432
	ds_read_b128 v[186:189], v149 offset:19456
	ds_read_b128 v[210:213], v149 offset:20480
	ds_read_b128 v[214:217], v149 offset:21504
	ds_read_b128 v[218:221], v149 offset:22528
	ds_read_b128 v[222:225], v149 offset:23552
	global_load_lds_dwordx4 v[190:191], off
	s_add_i32 m0, s26, 0x2000
	s_add_u32 s26, s58, 0x40000
	v_lshl_add_u64 v[194:195], s[58:59], 0, v[128:129]
	s_addc_u32 s27, s59, 0
	s_add_i32 s28, s29, s16
	global_load_lds_dwordx4 v[194:195], off
	v_lshl_add_u64 v[196:197], s[26:27], 0, v[192:193]
	s_mov_b32 m0, s28
	v_lshl_add_u64 v[200:201], s[62:63], 0, v[130:131]
	global_load_lds_dwordx4 v[196:197], off
	v_lshl_add_u64 v[196:197], s[26:27], 0, v[128:129]
	s_add_i32 m0, s28, 0x2000
	s_nop 0
	global_load_lds_dwordx4 v[196:197], off
	v_lshl_add_u64 v[196:197], s[62:63], 0, v[132:133]
	s_mov_b32 m0, s17
	s_nop 0
	global_load_lds_dwordx4 v[196:197], off
	s_mov_b32 m0, s18
	s_nop 0
	global_load_lds_dwordx4 v[200:201], off
	s_waitcnt vmcnt(8)
	s_waitcnt lgkmcnt(0)
	s_barrier
; #define PG8_STAGE(bufoff, gbase, voff) do { _Pragma("unroll") for (int _i = 0; _i < 2; ++_i) _Pragma("unroll") for (int _r = 0; _r < PG8_NREP; ++_r) \
;         __builtin_amdgcn_global_load_lds((const unsigned*)((const char*)(gbase) + (voff)[_i]), (PG8_LAS unsigned*)(lds + (bufoff) + ldsw + _i * 8192), 16, 0, 0); } while (0)
; #define PG8_LDA(dst, b, h) do { _Pragma("unroll") for (int m = 0; m < 4; ++m) _Pragma("unroll") for (int k = 0; k < 2; ++k) { dst[m][k] = *(const PG8_LAS bf16x8*)(lds + PG8_SA(b, h) + aoff + m * 2048 + k * 1024); PG8_DUP((unsigned)(uintptr_t)(lds + PG8_SA(b, h) + aoff + m * 2048 + k * 1024)); } } while (0)
; #define PG8_LDB(dst, b, h) do { _Pragma("unroll") for (int n = 0; n < 2; ++n) _Pragma("unroll") for (int k = 0; k < 2; ++k) { dst[n][k] = *(const PG8_LAS bf16x8*)(lds + PG8_SB(b, h) + boff + n * 2048 + k * 1024); PG8_DUP((unsigned)(uintptr_t)(lds + PG8_SB(b, h) + boff + n * 2048 + k * 1024)); } } while (0)
; #define PG8_MMA(ai, bj, At, Bt) do { __builtin_amdgcn_s_setprio(1); _Pragma("unroll") for (int m = 0; m < 4; ++m) _Pragma("unroll") for (int n = 0; n < 2; ++n) _Pragma("unroll") for (int k = 0; k < 2; ++k) \
;         acc[ai][bj][m][n] = __builtin_amdgcn_mfma_f32_16x16x32_bf16(Bt[n][k], At[m][k], acc[ai][bj][m][n], 0, 0, 0); __builtin_amdgcn_s_setprio(0); } while (0)
; #define PG8_WAIT_V(n) do { if ((n) == 0) asm volatile("s_waitcnt vmcnt(0)" ::: "memory"); else if ((n) == 2) asm volatile("s_waitcnt vmcnt(4)" ::: "memory"); else if ((n) == 4) asm volatile("s_waitcnt vmcnt(8)" ::: "memory"); \
;     else if ((n) == 6) asm volatile("s_waitcnt vmcnt(12)" ::: "memory"); else asm volatile("s_waitcnt vmcnt(16)" ::: "memory"); } while (0)
; #define PG8_WAIT_V(n) asm volatile("s_waitcnt vmcnt(" #n ")" ::: "memory")
; #define PG8_BAR __builtin_amdgcn_s_barrier()
; template <class Epi, class Sched, bool ALIGN_EPI = false, bool SP2 = false>
; __device__ __forceinline__ void gemm_phase(PG8_LAS unsigned char* lds, const Gemm g, const Sched& S, const Epi& E) {
;     ...
;             PG8_WAIT_V(8); PG8_WAIT_L(0); PG8_BAR; PG8_MMA(1, 0, At, B0); PG8_MMA(1, 1, At, B1); PG8_BAR; PG8_SCHED;
;             PG8_LDB(B0, 1, 0); PG8_LDB(B1, 1, 1); PG8_SCHED; PG8_LDA(At, 1, 0); PG8_STAGE(PG8_SA(0, 1), a2 + hstepA, voffA);
;             PG8_WAIT_V(8); PG8_WAIT_L(0); PG8_BAR; PG8_MMA(0, 0, At, B0); PG8_MMA(0, 1, At, B1); PG8_BAR; PG8_SCHED;
	s_setprio 1
	s_waitcnt lgkmcnt(0)
	v_mfma_f32_16x16x32_bf16 v[60:63], v[138:141], v[174:177], v[60:63]
	v_mfma_f32_16x16x32_bf16 v[56:59], v[150:153], v[174:177], v[56:59]
	v_mfma_f32_16x16x32_bf16 v[44:47], v[138:141], v[182:185], v[44:47]
	v_mfma_f32_16x16x32_bf16 v[40:43], v[150:153], v[182:185], v[40:43]
	v_mfma_f32_16x16x32_bf16 v[28:31], v[138:141], v[210:213], v[28:31]
	v_mfma_f32_16x16x32_bf16 v[24:27], v[150:153], v[210:213], v[24:27]
	v_mfma_f32_16x16x32_bf16 v[12:15], v[138:141], v[218:221], v[12:15]
	v_mfma_f32_16x16x32_bf16 v[8:11], v[150:153], v[218:221], v[8:11]
	v_mfma_f32_16x16x32_bf16 v[60:63], v[142:145], v[178:181], v[60:63]
	v_mfma_f32_16x16x32_bf16 v[56:59], v[154:157], v[178:181], v[56:59]
	v_mfma_f32_16x16x32_bf16 v[44:47], v[142:145], v[186:189], v[44:47]
	v_mfma_f32_16x16x32_bf16 v[40:43], v[154:157], v[186:189], v[40:43]
	v_mfma_f32_16x16x32_bf16 v[28:31], v[142:145], v[214:217], v[28:31]
	v_mfma_f32_16x16x32_bf16 v[24:27], v[154:157], v[214:217], v[24:27]
	v_mfma_f32_16x16x32_bf16 v[12:15], v[142:145], v[222:225], v[12:15]
	v_mfma_f32_16x16x32_bf16 v[8:11], v[154:157], v[222:225], v[8:11]
	s_setprio 0
	s_setprio 1
	v_mfma_f32_16x16x32_bf16 v[52:55], v[158:161], v[174:177], v[52:55]
	v_mfma_f32_16x16x32_bf16 v[48:51], v[166:169], v[174:177], v[48:51]
	v_mfma_f32_16x16x32_bf16 v[36:39], v[158:161], v[182:185], v[36:39]
	v_mfma_f32_16x16x32_bf16 v[32:35], v[166:169], v[182:185], v[32:35]
	v_mfma_f32_16x16x32_bf16 v[20:23], v[158:161], v[210:213], v[20:23]
	v_mfma_f32_16x16x32_bf16 v[16:19], v[166:169], v[210:213], v[16:19]
	v_mfma_f32_16x16x32_bf16 v[4:7], v[158:161], v[218:221], v[4:7]
	v_mfma_f32_16x16x32_bf16 v[0:3], v[166:169], v[218:221], v[0:3]
	v_mfma_f32_16x16x32_bf16 v[52:55], v[162:165], v[178:181], v[52:55]
	v_mfma_f32_16x16x32_bf16 v[48:51], v[170:173], v[178:181], v[48:51]
	v_mfma_f32_16x16x32_bf16 v[36:39], v[162:165], v[186:189], v[36:39]
	v_mfma_f32_16x16x32_bf16 v[32:35], v[170:173], v[186:189], v[32:35]
	v_mfma_f32_16x16x32_bf16 v[20:23], v[162:165], v[214:217], v[20:23]
	v_mfma_f32_16x16x32_bf16 v[16:19], v[170:173], v[214:217], v[16:19]
	v_mfma_f32_16x16x32_bf16 v[4:7], v[162:165], v[222:225], v[4:7]
	v_mfma_f32_16x16x32_bf16 v[0:3], v[170:173], v[222:225], v[0:3]
	s_setprio 0
	s_barrier
	s_add_i32 s28, 0, 0x18000
	s_add_i32 s29, 0, 0x1c000
	v_add_u32_e32 v154, s28, v147
	v_add_u32_e32 v170, s29, v147
	ds_read_b128 v[138:141], v154
	ds_read_b128 v[142:145], v154 offset:1024
	ds_read_b128 v[150:153], v154 offset:2048
	ds_read_b128 v[154:157], v154 offset:3072
	ds_read_b128 v[158:161], v170
	ds_read_b128 v[162:165], v170 offset:1024
	ds_read_b128 v[166:169], v170 offset:2048
	ds_read_b128 v[170:173], v170 offset:3072
	s_add_u32 s26, s62, 0x40000
	s_addc_u32 s27, s63, 0
	s_mov_b32 m0, s19
	v_lshl_add_u64 v[226:227], s[26:27], 0, v[132:133]
	ds_read_b128 v[174:177], v149 offset:32768
	ds_read_b128 v[178:181], v149 offset:33792
	ds_read_b128 v[182:185], v149 offset:34816
	ds_read_b128 v[186:189], v149 offset:35840
	ds_read_b128 v[210:213], v149 offset:36864
	ds_read_b128 v[214:217], v149 offset:37888
	ds_read_b128 v[218:221], v149 offset:38912
	ds_read_b128 v[222:225], v149 offset:39936
	global_load_lds_dwordx4 v[226:227], off
	v_lshl_add_u64 v[226:227], s[26:27], 0, v[130:131]
	s_mov_b32 m0, s20
	s_nop 0
	global_load_lds_dwordx4 v[226:227], off
	s_waitcnt vmcnt(8)
	s_waitcnt lgkmcnt(0)
	s_barrier
	s_setprio 1
	s_waitcnt lgkmcnt(0)
	v_mfma_f32_16x16x32_bf16 v[124:127], v[138:141], v[174:177], v[124:127]
	v_mfma_f32_16x16x32_bf16 v[120:123], v[150:153], v[174:177], v[120:123]
	v_mfma_f32_16x16x32_bf16 v[108:111], v[138:141], v[182:185], v[108:111]
	v_mfma_f32_16x16x32_bf16 v[104:107], v[150:153], v[182:185], v[104:107]
	v_mfma_f32_16x16x32_bf16 v[92:95], v[138:141], v[210:213], v[92:95]
	v_mfma_f32_16x16x32_bf16 v[88:91], v[150:153], v[210:213], v[88:91]
	v_mfma_f32_16x16x32_bf16 v[76:79], v[138:141], v[218:221], v[76:79]
	v_mfma_f32_16x16x32_bf16 v[72:75], v[150:153], v[218:221], v[72:75]
	v_mfma_f32_16x16x32_bf16 v[124:127], v[142:145], v[178:181], v[124:127]
	v_mfma_f32_16x16x32_bf16 v[120:123], v[154:157], v[178:181], v[120:123]
	v_mfma_f32_16x16x32_bf16 v[108:111], v[142:145], v[186:189], v[108:111]
	v_mfma_f32_16x16x32_bf16 v[104:107], v[154:157], v[186:189], v[104:107]
	v_mfma_f32_16x16x32_bf16 v[92:95], v[142:145], v[214:217], v[92:95]
	v_mfma_f32_16x16x32_bf16 v[88:91], v[154:157], v[214:217], v[88:91]
	v_mfma_f32_16x16x32_bf16 v[76:79], v[142:145], v[222:225], v[76:79]
	v_mfma_f32_16x16x32_bf16 v[72:75], v[154:157], v[222:225], v[72:75]
	s_setprio 0
	s_setprio 1
	v_mfma_f32_16x16x32_bf16 v[116:119], v[158:161], v[174:177], v[116:119]
	v_mfma_f32_16x16x32_bf16 v[112:115], v[166:169], v[174:177], v[112:115]
	v_mfma_f32_16x16x32_bf16 v[100:103], v[158:161], v[182:185], v[100:103]
	v_mfma_f32_16x16x32_bf16 v[96:99], v[166:169], v[182:185], v[96:99]
	v_mfma_f32_16x16x32_bf16 v[84:87], v[158:161], v[210:213], v[84:87]
	v_mfma_f32_16x16x32_bf16 v[80:83], v[166:169], v[210:213], v[80:83]
	v_mfma_f32_16x16x32_bf16 v[68:71], v[158:161], v[218:221], v[68:71]
	v_mfma_f32_16x16x32_bf16 v[64:67], v[166:169], v[218:221], v[64:67]
	v_mfma_f32_16x16x32_bf16 v[116:119], v[162:165], v[178:181], v[116:119]
	v_mfma_f32_16x16x32_bf16 v[112:115], v[170:173], v[178:181], v[112:115]
	v_mfma_f32_16x16x32_bf16 v[100:103], v[162:165], v[186:189], v[100:103]
	v_mfma_f32_16x16x32_bf16 v[96:99], v[170:173], v[186:189], v[96:99]
	v_mfma_f32_16x16x32_bf16 v[84:87], v[162:165], v[214:217], v[84:87]
	v_mfma_f32_16x16x32_bf16 v[80:83], v[170:173], v[214:217], v[80:83]
	v_mfma_f32_16x16x32_bf16 v[68:71], v[162:165], v[222:225], v[68:71]
	v_mfma_f32_16x16x32_bf16 v[64:67], v[170:173], v[222:225], v[64:67]
	s_setprio 0
	s_barrier
; #define PG8_STAGE(bufoff, gbase, voff) do { _Pragma("unroll") for (int _i = 0; _i < 2; ++_i) _Pragma("unroll") for (int _r = 0; _r < PG8_NREP; ++_r) \
;         __builtin_amdgcn_global_load_lds((const unsigned*)((const char*)(gbase) + (voff)[_i]), (PG8_LAS unsigned*)(lds + (bufoff) + ldsw + _i * 8192), 16, 0, 0); } while (0)
; #define PG8_LDA(dst, b, h) do { _Pragma("unroll") for (int m = 0; m < 4; ++m) _Pragma("unroll") for (int k = 0; k < 2; ++k) { dst[m][k] = *(const PG8_LAS bf16x8*)(lds + PG8_SA(b, h) + aoff + m * 2048 + k * 1024); PG8_DUP((unsigned)(uintptr_t)(lds + PG8_SA(b, h) + aoff + m * 2048 + k * 1024)); } } while (0)
; #define PG8_MMA(ai, bj, At, Bt) do { __builtin_amdgcn_s_setprio(1); _Pragma("unroll") for (int m = 0; m < 4; ++m) _Pragma("unroll") for (int n = 0; n < 2; ++n) _Pragma("unroll") for (int k = 0; k < 2; ++k) \
;         acc[ai][bj][m][n] = __builtin_amdgcn_mfma_f32_16x16x32_bf16(Bt[n][k], At[m][k], acc[ai][bj][m][n], 0, 0, 0); __builtin_amdgcn_s_setprio(0); } while (0)
; #define PG8_WAIT_V(n) do { if ((n) == 0) asm volatile("s_waitcnt vmcnt(0)" ::: "memory"); else if ((n) == 2) asm volatile("s_waitcnt vmcnt(4)" ::: "memory"); else if ((n) == 4) asm volatile("s_waitcnt vmcnt(8)" ::: "memory"); \
;     else if ((n) == 6) asm volatile("s_waitcnt vmcnt(12)" ::: "memory"); else asm volatile("s_waitcnt vmcnt(16)" ::: "memory"); } while (0)
; #define PG8_WAIT_V(n) asm volatile("s_waitcnt vmcnt(" #n ")" ::: "memory")
; #define PG8_WAIT_L(n) asm volatile("s_waitcnt lgkmcnt(" #n ")" ::: "memory")
; #define PG8_BAR __builtin_amdgcn_s_barrier()
; #define PG8_SCHED __builtin_amdgcn_sched_barrier(0)
; template <class Epi, class Sched, bool ALIGN_EPI = false, bool SP2 = false>
; __device__ __forceinline__ void gemm_phase(PG8_LAS unsigned char* lds, const Gemm g, const Sched& S, const Epi& E) {
;     ...
;             PG8_LDA(At, 1, 1); PG8_STAGE(PG8_SB(1, 0), b3, voffB); PG8_STAGE(PG8_SB(1, 1), b3 + hstepB, voffB); PG8_STAGE(PG8_SA(1, 0), a3, voffA);
;             PG8_WAIT_V(8); PG8_WAIT_L(0); PG8_BAR; PG8_MMA(1, 0, At, B0); PG8_MMA(1, 1, At, B1); PG8_BAR; PG8_SCHED;
;     ...
;         if constexpr (ALIGN_EPI) { if (wr == 0) PG8_BAR; }
	s_add_i32 s26, s28, s16
	v_lshl_add_u64 v[190:191], v[190:191], 0, s[68:69]
	s_mov_b32 m0, s26
	ds_read_b128 v[174:177], v149 offset:49152
	ds_read_b128 v[178:181], v149 offset:50176
	ds_read_b128 v[182:185], v149 offset:51200
	ds_read_b128 v[186:189], v149 offset:52224
	ds_read_b128 v[210:213], v149 offset:53248
	ds_read_b128 v[214:217], v149 offset:54272
	ds_read_b128 v[218:221], v149 offset:55296
	ds_read_b128 v[222:225], v149 offset:56320
	global_load_lds_dwordx4 v[190:191], off
	s_add_i32 m0, s26, 0x2000
	s_add_u32 s26, s58, 0x40080
	v_lshl_add_u64 v[190:191], v[194:195], 0, s[68:69]
	s_addc_u32 s27, s59, 0
	s_add_i32 s28, s29, s16
	global_load_lds_dwordx4 v[190:191], off
	v_lshl_add_u64 v[190:191], s[26:27], 0, v[192:193]
	s_mov_b32 m0, s28
	s_nop 0
	global_load_lds_dwordx4 v[190:191], off
	v_lshl_add_u64 v[190:191], s[26:27], 0, v[128:129]
	s_add_i32 m0, s28, 0x2000
	s_nop 0
	global_load_lds_dwordx4 v[190:191], off
	v_lshl_add_u64 v[190:191], v[196:197], 0, s[68:69]
	s_mov_b32 m0, s21
	s_nop 0
	global_load_lds_dwordx4 v[190:191], off
	v_lshl_add_u64 v[190:191], v[200:201], 0, s[68:69]
	s_mov_b32 m0, s22
	s_nop 0
	global_load_lds_dwordx4 v[190:191], off
	s_waitcnt vmcnt(8)
	s_waitcnt lgkmcnt(0)
	s_barrier
	s_setprio 1
	s_waitcnt lgkmcnt(0)
	v_mfma_f32_16x16x32_bf16 v[60:63], v[138:141], v[174:177], v[60:63]
	v_mfma_f32_16x16x32_bf16 v[56:59], v[150:153], v[174:177], v[56:59]
	v_mfma_f32_16x16x32_bf16 v[44:47], v[138:141], v[182:185], v[44:47]
	v_mfma_f32_16x16x32_bf16 v[40:43], v[150:153], v[182:185], v[40:43]
	v_mfma_f32_16x16x32_bf16 v[28:31], v[138:141], v[210:213], v[28:31]
	v_mfma_f32_16x16x32_bf16 v[24:27], v[150:153], v[210:213], v[24:27]
	v_mfma_f32_16x16x32_bf16 v[12:15], v[138:141], v[218:221], v[12:15]
	v_mfma_f32_16x16x32_bf16 v[8:11], v[150:153], v[218:221], v[8:11]
	v_mfma_f32_16x16x32_bf16 v[60:63], v[142:145], v[178:181], v[60:63]
	v_mfma_f32_16x16x32_bf16 v[56:59], v[154:157], v[178:181], v[56:59]
	v_mfma_f32_16x16x32_bf16 v[44:47], v[142:145], v[186:189], v[44:47]
	v_mfma_f32_16x16x32_bf16 v[40:43], v[154:157], v[186:189], v[40:43]
	v_mfma_f32_16x16x32_bf16 v[28:31], v[142:145], v[214:217], v[28:31]
	v_mfma_f32_16x16x32_bf16 v[24:27], v[154:157], v[214:217], v[24:27]
	v_mfma_f32_16x16x32_bf16 v[12:15], v[142:145], v[222:225], v[12:15]
	v_mfma_f32_16x16x32_bf16 v[8:11], v[154:157], v[222:225], v[8:11]
	s_setprio 0
	s_setprio 1
	v_mfma_f32_16x16x32_bf16 v[52:55], v[158:161], v[174:177], v[52:55]
	v_mfma_f32_16x16x32_bf16 v[48:51], v[166:169], v[174:177], v[48:51]
	v_mfma_f32_16x16x32_bf16 v[36:39], v[158:161], v[182:185], v[36:39]
	v_mfma_f32_16x16x32_bf16 v[32:35], v[166:169], v[182:185], v[32:35]
	v_mfma_f32_16x16x32_bf16 v[20:23], v[158:161], v[210:213], v[20:23]
	v_mfma_f32_16x16x32_bf16 v[16:19], v[166:169], v[210:213], v[16:19]
	v_mfma_f32_16x16x32_bf16 v[4:7], v[158:161], v[218:221], v[4:7]
	v_mfma_f32_16x16x32_bf16 v[0:3], v[166:169], v[218:221], v[0:3]
	v_mfma_f32_16x16x32_bf16 v[52:55], v[162:165], v[178:181], v[52:55]
	v_mfma_f32_16x16x32_bf16 v[48:51], v[170:173], v[178:181], v[48:51]
	v_mfma_f32_16x16x32_bf16 v[36:39], v[162:165], v[186:189], v[36:39]
	v_mfma_f32_16x16x32_bf16 v[32:35], v[170:173], v[186:189], v[32:35]
	v_mfma_f32_16x16x32_bf16 v[20:23], v[162:165], v[214:217], v[20:23]
	v_mfma_f32_16x16x32_bf16 v[16:19], v[170:173], v[214:217], v[16:19]
	v_mfma_f32_16x16x32_bf16 v[4:7], v[162:165], v[222:225], v[4:7]
	v_mfma_f32_16x16x32_bf16 v[0:3], v[170:173], v[222:225], v[0:3]
	s_setprio 0
	s_add_i32 s25, s25, 2
	s_add_u32 s54, s54, 0x100
	s_addc_u32 s55, s55, 0
	s_add_u32 s94, s94, 0x100
	s_addc_u32 s24, s24, 0
	s_cmp_gt_u32 s25, 13
	s_barrier
	s_cbranch_scc0 .LBB0_612
	s_and_b64 vcc, exec, s[40:41]
	s_cbranch_vccz .LBB0_615
	s_barrier

; #define PG8_STAGE(bufoff, gbase, voff) do { _Pragma("unroll") for (int _i = 0; _i < 2; ++_i) _Pragma("unroll") for (int _r = 0; _r < PG8_NREP; ++_r) \
;         __builtin_amdgcn_global_load_lds((const unsigned*)((const char*)(gbase) + (voff)[_i]), (PG8_LAS unsigned*)(lds + (bufoff) + ldsw + _i * 8192), 16, 0, 0); } while (0)
; #define PG8_LDA(dst, b, h) do { _Pragma("unroll") for (int m = 0; m < 4; ++m) _Pragma("unroll") for (int k = 0; k < 2; ++k) { dst[m][k] = *(const PG8_LAS bf16x8*)(lds + PG8_SA(b, h) + aoff + m * 2048 + k * 1024); PG8_DUP((unsigned)(uintptr_t)(lds + PG8_SA(b, h) + aoff + m * 2048 + k * 1024)); } } while (0)
; #define PG8_LDB(dst, b, h) do { _Pragma("unroll") for (int n = 0; n < 2; ++n) _Pragma("unroll") for (int k = 0; k < 2; ++k) { dst[n][k] = *(const PG8_LAS bf16x8*)(lds + PG8_SB(b, h) + boff + n * 2048 + k * 1024); PG8_DUP((unsigned)(uintptr_t)(lds + PG8_SB(b, h) + boff + n * 2048 + k * 1024)); } } while (0)
; #define PG8_MMA(ai, bj, At, Bt) do { __builtin_amdgcn_s_setprio(1); _Pragma("unroll") for (int m = 0; m < 4; ++m) _Pragma("unroll") for (int n = 0; n < 2; ++n) _Pragma("unroll") for (int k = 0; k < 2; ++k) \
;         acc[ai][bj][m][n] = __builtin_amdgcn_mfma_f32_16x16x32_bf16(Bt[n][k], At[m][k], acc[ai][bj][m][n], 0, 0, 0); __builtin_amdgcn_s_setprio(0); } while (0)
; template <class Epi, class Sched, bool ALIGN_EPI = false, bool SP2 = false>
; __device__ __forceinline__ void gemm_phase(PG8_LAS unsigned char* lds, const Gemm g, const Sched& S, const Epi& E) {
;     ...
;             const bool last = (t == nt - 2);
;             const char* a1 = cA + (size_t)(t + 1) * kstep;
;             const char* a2 = last ? nA : cA + (size_t)(t + 2) * kstep; const char* b2 = last ? nB : cB + (size_t)(t + 2) * kstep;
;             const char* a3 = a2 + kstep; const char* b3 = b2 + kstep;
;             if (last && has_next) S.a_ready(nxt);
;             if constexpr (SP2) {
;     ...
;             if (Epi::PERM && sizeof(Epi) && TEST_DRAIN) PG8_WAIT_V(0);
;     ...
;             PG8_LDB(B0, 0, 0); PG8_LDB(B1, 0, 1); PG8_SCHED; PG8_LDA(At, 0, 0); PG8_STAGE(PG8_SA(1, 1), a1 + hstepA, voffA);
;             PG8_WAIT_V(8); PG8_WAIT_L(0); PG8_BAR; PG8_MMA(0, 0, At, B0); PG8_MMA(0, 1, At, B1); PG8_BAR; PG8_SCHED;
;             PG8_LDA(At, 0, 1); PG8_STAGE(PG8_SB(0, 0), b2, voffB); PG8_STAGE(PG8_SB(0, 1), b2 + hstepB, voffB); PG8_STAGE(PG8_SA(0, 0), a2, voffA);
.LBB0_684:
	s_add_u32 s26, s14, 0xfff80080
	s_addc_u32 s27, s15, -1
	s_add_i32 s28, 0, 0x10000
	s_cmp_eq_u32 s25, 28
	s_cselect_b32 s95, s23, s27
	s_cselect_b32 s94, s63, s26
	s_cselect_b32 s93, s55, s24
	s_cselect_b32 s92, vcc_lo, vcc_hi
	s_add_i32 s29, 0, 0x14000
	v_add_u32_e32 v52, s28, v165
	v_add_u32_e32 v162, s29, v165
	ds_read_b128 v[24:27], v52
	ds_read_b128 v[28:31], v52 offset:1024
	ds_read_b128 v[48:51], v52 offset:2048
	ds_read_b128 v[52:55], v52 offset:3072
	ds_read_b128 v[154:157], v162
	ds_read_b128 v[158:161], v162 offset:1024
	ds_read_b128 v[168:171], v162 offset:2048
	ds_read_b128 v[172:175], v162 offset:3072
	v_lshl_add_u64 v[162:163], s[14:15], 0, v[150:151]
	s_add_i32 m0, s91, 0xc000
	ds_read_b128 v[176:179], v167
	ds_read_b128 v[180:183], v167 offset:1024
	ds_read_b128 v[184:187], v167 offset:2048
	ds_read_b128 v[188:191], v167 offset:3072
	ds_read_b128 v[210:213], v167 offset:4096
	ds_read_b128 v[214:217], v167 offset:5120
	ds_read_b128 v[218:221], v167 offset:6144
	ds_read_b128 v[222:225], v167 offset:7168
	global_load_lds_dwordx4 v[162:163], off
	v_lshl_add_u64 v[162:163], s[14:15], 0, v[152:153]
	s_add_i32 m0, s91, 0xe000
	s_nop 0
	global_load_lds_dwordx4 v[162:163], off
	s_waitcnt vmcnt(8)
	s_waitcnt lgkmcnt(0)
	s_barrier
	s_setprio 1
	s_waitcnt lgkmcnt(0)
	v_mfma_f32_16x16x32_bf16 v[140:143], v[24:27], v[176:179], v[140:143]
	v_mfma_f32_16x16x32_bf16 v[136:139], v[48:51], v[176:179], v[136:139]
	v_mfma_f32_16x16x32_bf16 v[124:127], v[24:27], v[184:187], v[124:127]
	v_mfma_f32_16x16x32_bf16 v[120:123], v[48:51], v[184:187], v[120:123]
	v_mfma_f32_16x16x32_bf16 v[108:111], v[24:27], v[210:213], v[108:111]
	v_mfma_f32_16x16x32_bf16 v[104:107], v[48:51], v[210:213], v[104:107]
	v_mfma_f32_16x16x32_bf16 v[92:95], v[24:27], v[218:221], v[92:95]
	v_mfma_f32_16x16x32_bf16 v[88:91], v[48:51], v[218:221], v[88:91]
	v_mfma_f32_16x16x32_bf16 v[140:143], v[28:31], v[180:183], v[140:143]
	v_mfma_f32_16x16x32_bf16 v[136:139], v[52:55], v[180:183], v[136:139]
	v_mfma_f32_16x16x32_bf16 v[124:127], v[28:31], v[188:191], v[124:127]
	v_mfma_f32_16x16x32_bf16 v[120:123], v[52:55], v[188:191], v[120:123]
	v_mfma_f32_16x16x32_bf16 v[108:111], v[28:31], v[214:217], v[108:111]
	v_mfma_f32_16x16x32_bf16 v[104:107], v[52:55], v[214:217], v[104:107]
	v_mfma_f32_16x16x32_bf16 v[92:95], v[28:31], v[222:225], v[92:95]
	v_mfma_f32_16x16x32_bf16 v[88:91], v[52:55], v[222:225], v[88:91]
	s_setprio 0
	s_setprio 1
	v_mfma_f32_16x16x32_bf16 v[132:135], v[154:157], v[176:179], v[132:135]
	v_mfma_f32_16x16x32_bf16 v[128:131], v[168:171], v[176:179], v[128:131]
	v_mfma_f32_16x16x32_bf16 v[116:119], v[154:157], v[184:187], v[116:119]
	v_mfma_f32_16x16x32_bf16 v[112:115], v[168:171], v[184:187], v[112:115]
	v_mfma_f32_16x16x32_bf16 v[100:103], v[154:157], v[210:213], v[100:103]
	v_mfma_f32_16x16x32_bf16 v[96:99], v[168:171], v[210:213], v[96:99]
	v_mfma_f32_16x16x32_bf16 v[84:87], v[154:157], v[218:221], v[84:87]
	v_mfma_f32_16x16x32_bf16 v[80:83], v[168:171], v[218:221], v[80:83]
	v_mfma_f32_16x16x32_bf16 v[132:135], v[158:161], v[180:183], v[132:135]
	v_mfma_f32_16x16x32_bf16 v[128:131], v[172:175], v[180:183], v[128:131]
	v_mfma_f32_16x16x32_bf16 v[116:119], v[158:161], v[188:191], v[116:119]
	v_mfma_f32_16x16x32_bf16 v[112:115], v[172:175], v[188:191], v[112:115]
	v_mfma_f32_16x16x32_bf16 v[100:103], v[158:161], v[214:217], v[100:103]
	v_mfma_f32_16x16x32_bf16 v[96:99], v[172:175], v[214:217], v[96:99]
	v_mfma_f32_16x16x32_bf16 v[84:87], v[158:161], v[222:225], v[84:87]
	v_mfma_f32_16x16x32_bf16 v[80:83], v[172:175], v[222:225], v[80:83]
	s_setprio 0
	s_barrier
	s_add_i32 s26, s28, s86
	v_lshl_add_u64 v[162:163], s[92:93], 0, v[192:193]
	s_mov_b32 m0, s26
	ds_read_b128 v[176:179], v167 offset:16384
	ds_read_b128 v[180:183], v167 offset:17408
	ds_read_b128 v[184:187], v167 offset:18432
	ds_read_b128 v[188:191], v167 offset:19456
	ds_read_b128 v[210:213], v167 offset:20480
	ds_read_b128 v[214:217], v167 offset:21504
	ds_read_b128 v[218:221], v167 offset:22528
	ds_read_b128 v[222:225], v167 offset:23552
	global_load_lds_dwordx4 v[162:163], off
	s_add_i32 m0, s26, 0x2000
	s_add_u32 s26, s92, 0x80000
	v_lshl_add_u64 v[194:195], s[92:93], 0, v[144:145]
	s_addc_u32 s27, s93, 0
	s_add_i32 s28, s29, s86
	global_load_lds_dwordx4 v[194:195], off
	v_lshl_add_u64 v[196:197], s[26:27], 0, v[192:193]
	s_mov_b32 m0, s28
	v_lshl_add_u64 v[200:201], s[94:95], 0, v[146:147]
	global_load_lds_dwordx4 v[196:197], off
	v_lshl_add_u64 v[196:197], s[26:27], 0, v[144:145]
	s_add_i32 m0, s28, 0x2000
	s_nop 0
	global_load_lds_dwordx4 v[196:197], off
	v_lshl_add_u64 v[196:197], s[94:95], 0, v[148:149]
	s_mov_b32 m0, s91
	s_nop 0
	global_load_lds_dwordx4 v[196:197], off
	s_mov_b32 m0, s97
	s_nop 0
	global_load_lds_dwordx4 v[200:201], off
	s_waitcnt vmcnt(8)
	s_waitcnt lgkmcnt(0)
	s_barrier
; #define PG8_STAGE(bufoff, gbase, voff) do { _Pragma("unroll") for (int _i = 0; _i < 2; ++_i) _Pragma("unroll") for (int _r = 0; _r < PG8_NREP; ++_r) \
;         __builtin_amdgcn_global_load_lds((const unsigned*)((const char*)(gbase) + (voff)[_i]), (PG8_LAS unsigned*)(lds + (bufoff) + ldsw + _i * 8192), 16, 0, 0); } while (0)
; #define PG8_LDA(dst, b, h) do { _Pragma("unroll") for (int m = 0; m < 4; ++m) _Pragma("unroll") for (int k = 0; k < 2; ++k) { dst[m][k] = *(const PG8_LAS bf16x8*)(lds + PG8_SA(b, h) + aoff + m * 2048 + k * 1024); PG8_DUP((unsigned)(uintptr_t)(lds + PG8_SA(b, h) + aoff + m * 2048 + k * 1024)); } } while (0)
; #define PG8_LDB(dst, b, h) do { _Pragma("unroll") for (int n = 0; n < 2; ++n) _Pragma("unroll") for (int k = 0; k < 2; ++k) { dst[n][k] = *(const PG8_LAS bf16x8*)(lds + PG8_SB(b, h) + boff + n * 2048 + k * 1024); PG8_DUP((unsigned)(uintptr_t)(lds + PG8_SB(b, h) + boff + n * 2048 + k * 1024)); } } while (0)
; #define PG8_MMA(ai, bj, At, Bt) do { __builtin_amdgcn_s_setprio(1); _Pragma("unroll") for (int m = 0; m < 4; ++m) _Pragma("unroll") for (int n = 0; n < 2; ++n) _Pragma("unroll") for (int k = 0; k < 2; ++k) \
;         acc[ai][bj][m][n] = __builtin_amdgcn_mfma_f32_16x16x32_bf16(Bt[n][k], At[m][k], acc[ai][bj][m][n], 0, 0, 0); __builtin_amdgcn_s_setprio(0); } while (0)
; #define PG8_WAIT_V(n) do { if ((n) == 0) asm volatile("s_waitcnt vmcnt(0)" ::: "memory"); else if ((n) == 2) asm volatile("s_waitcnt vmcnt(4)" ::: "memory"); else if ((n) == 4) asm volatile("s_waitcnt vmcnt(8)" ::: "memory"); \
;     else if ((n) == 6) asm volatile("s_waitcnt vmcnt(12)" ::: "memory"); else asm volatile("s_waitcnt vmcnt(16)" ::: "memory"); } while (0)
; #define PG8_WAIT_V(n) asm volatile("s_waitcnt vmcnt(" #n ")" ::: "memory")
; #define PG8_BAR __builtin_amdgcn_s_barrier()
; template <class Epi, class Sched, bool ALIGN_EPI = false, bool SP2 = false>
; __device__ __forceinline__ void gemm_phase(PG8_LAS unsigned char* lds, const Gemm g, const Sched& S, const Epi& E) {
;     ...
;             PG8_WAIT_V(8); PG8_WAIT_L(0); PG8_BAR; PG8_MMA(1, 0, At, B0); PG8_MMA(1, 1, At, B1); PG8_BAR; PG8_SCHED;
;             PG8_LDB(B0, 1, 0); PG8_LDB(B1, 1, 1); PG8_SCHED; PG8_LDA(At, 1, 0); PG8_STAGE(PG8_SA(0, 1), a2 + hstepA, voffA);
;             PG8_WAIT_V(8); PG8_WAIT_L(0); PG8_BAR; PG8_MMA(0, 0, At, B0); PG8_MMA(0, 1, At, B1); PG8_BAR; PG8_SCHED;
	s_setprio 1
	s_waitcnt lgkmcnt(0)
	v_mfma_f32_16x16x32_bf16 v[76:79], v[24:27], v[176:179], v[76:79]
	v_mfma_f32_16x16x32_bf16 v[72:75], v[48:51], v[176:179], v[72:75]
	v_mfma_f32_16x16x32_bf16 v[60:63], v[24:27], v[184:187], v[60:63]
	v_mfma_f32_16x16x32_bf16 v[56:59], v[48:51], v[184:187], v[56:59]
	v_mfma_f32_16x16x32_bf16 v[36:39], v[24:27], v[210:213], v[36:39]
	v_mfma_f32_16x16x32_bf16 v[32:35], v[48:51], v[210:213], v[32:35]
	v_mfma_f32_16x16x32_bf16 v[12:15], v[24:27], v[218:221], v[12:15]
	v_mfma_f32_16x16x32_bf16 v[8:11], v[48:51], v[218:221], v[8:11]
	v_mfma_f32_16x16x32_bf16 v[76:79], v[28:31], v[180:183], v[76:79]
	v_mfma_f32_16x16x32_bf16 v[72:75], v[52:55], v[180:183], v[72:75]
	v_mfma_f32_16x16x32_bf16 v[60:63], v[28:31], v[188:191], v[60:63]
	v_mfma_f32_16x16x32_bf16 v[56:59], v[52:55], v[188:191], v[56:59]
	v_mfma_f32_16x16x32_bf16 v[36:39], v[28:31], v[214:217], v[36:39]
	v_mfma_f32_16x16x32_bf16 v[32:35], v[52:55], v[214:217], v[32:35]
	v_mfma_f32_16x16x32_bf16 v[12:15], v[28:31], v[222:225], v[12:15]
	v_mfma_f32_16x16x32_bf16 v[8:11], v[52:55], v[222:225], v[8:11]
	s_setprio 0
	s_setprio 1
	v_mfma_f32_16x16x32_bf16 v[44:47], v[154:157], v[184:187], v[44:47]
	v_mfma_f32_16x16x32_bf16 v[40:43], v[168:171], v[184:187], v[40:43]
	v_mfma_f32_16x16x32_bf16 v[20:23], v[154:157], v[210:213], v[20:23]
	v_mfma_f32_16x16x32_bf16 v[16:19], v[168:171], v[210:213], v[16:19]
	v_mfma_f32_16x16x32_bf16 v[4:7], v[154:157], v[218:221], v[4:7]
	v_mfma_f32_16x16x32_bf16 v[0:3], v[168:171], v[218:221], v[0:3]
	v_mfma_f32_16x16x32_bf16 v[24:27], v[154:157], v[176:179], v[68:71]
	v_mfma_f32_16x16x32_bf16 v[28:31], v[168:171], v[176:179], v[64:67]
	v_mfma_f32_16x16x32_bf16 v[44:47], v[158:161], v[188:191], v[44:47]
	v_mfma_f32_16x16x32_bf16 v[40:43], v[172:175], v[188:191], v[40:43]
	v_mfma_f32_16x16x32_bf16 v[20:23], v[158:161], v[214:217], v[20:23]
	v_mfma_f32_16x16x32_bf16 v[16:19], v[172:175], v[214:217], v[16:19]
	v_mfma_f32_16x16x32_bf16 v[4:7], v[158:161], v[222:225], v[4:7]
	v_mfma_f32_16x16x32_bf16 v[0:3], v[172:175], v[222:225], v[0:3]
	v_mfma_f32_16x16x32_bf16 v[24:27], v[158:161], v[180:183], v[24:27]
	v_mfma_f32_16x16x32_bf16 v[28:31], v[172:175], v[180:183], v[28:31]
	s_setprio 0
	s_barrier
	s_add_i32 s28, 0, 0x18000
	s_add_i32 s29, 0, 0x1c000
	v_add_u32_e32 v68, s28, v165
	v_add_u32_e32 v172, s29, v165
	ds_read_b128 v[48:51], v68
	ds_read_b128 v[52:55], v68 offset:1024
	ds_read_b128 v[64:67], v68 offset:2048
	ds_read_b128 v[68:71], v68 offset:3072
	ds_read_b128 v[154:157], v172
	ds_read_b128 v[158:161], v172 offset:1024
	ds_read_b128 v[168:171], v172 offset:2048
	ds_read_b128 v[172:175], v172 offset:3072
	s_add_u32 s26, s94, 0x80000
	s_addc_u32 s27, s95, 0
	s_mov_b32 m0, s16
	v_lshl_add_u64 v[226:227], s[26:27], 0, v[148:149]
	ds_read_b128 v[176:179], v167 offset:32768
	ds_read_b128 v[180:183], v167 offset:33792
	ds_read_b128 v[184:187], v167 offset:34816
	ds_read_b128 v[188:191], v167 offset:35840
	ds_read_b128 v[210:213], v167 offset:36864
	ds_read_b128 v[214:217], v167 offset:37888
	ds_read_b128 v[218:221], v167 offset:38912
	ds_read_b128 v[222:225], v167 offset:39936
	global_load_lds_dwordx4 v[226:227], off
	v_lshl_add_u64 v[226:227], s[26:27], 0, v[146:147]
	s_mov_b32 m0, s17
	s_nop 0
	global_load_lds_dwordx4 v[226:227], off
	s_waitcnt vmcnt(8)
	s_waitcnt lgkmcnt(0)
	s_barrier
	s_setprio 1
	s_waitcnt lgkmcnt(0)
	v_mfma_f32_16x16x32_bf16 v[140:143], v[48:51], v[176:179], v[140:143]
	v_mfma_f32_16x16x32_bf16 v[136:139], v[64:67], v[176:179], v[136:139]
	v_mfma_f32_16x16x32_bf16 v[124:127], v[48:51], v[184:187], v[124:127]
	v_mfma_f32_16x16x32_bf16 v[120:123], v[64:67], v[184:187], v[120:123]
	v_mfma_f32_16x16x32_bf16 v[108:111], v[48:51], v[210:213], v[108:111]
	v_mfma_f32_16x16x32_bf16 v[104:107], v[64:67], v[210:213], v[104:107]
	v_mfma_f32_16x16x32_bf16 v[92:95], v[48:51], v[218:221], v[92:95]
	v_mfma_f32_16x16x32_bf16 v[88:91], v[64:67], v[218:221], v[88:91]
	v_mfma_f32_16x16x32_bf16 v[140:143], v[52:55], v[180:183], v[140:143]
	v_mfma_f32_16x16x32_bf16 v[136:139], v[68:71], v[180:183], v[136:139]
	v_mfma_f32_16x16x32_bf16 v[124:127], v[52:55], v[188:191], v[124:127]
	v_mfma_f32_16x16x32_bf16 v[120:123], v[68:71], v[188:191], v[120:123]
	v_mfma_f32_16x16x32_bf16 v[108:111], v[52:55], v[214:217], v[108:111]
	v_mfma_f32_16x16x32_bf16 v[104:107], v[68:71], v[214:217], v[104:107]
	v_mfma_f32_16x16x32_bf16 v[92:95], v[52:55], v[222:225], v[92:95]
	v_mfma_f32_16x16x32_bf16 v[88:91], v[68:71], v[222:225], v[88:91]
	s_setprio 0
	s_setprio 1
	v_mfma_f32_16x16x32_bf16 v[132:135], v[154:157], v[176:179], v[132:135]
	v_mfma_f32_16x16x32_bf16 v[128:131], v[168:171], v[176:179], v[128:131]
	v_mfma_f32_16x16x32_bf16 v[116:119], v[154:157], v[184:187], v[116:119]
	v_mfma_f32_16x16x32_bf16 v[112:115], v[168:171], v[184:187], v[112:115]
	v_mfma_f32_16x16x32_bf16 v[100:103], v[154:157], v[210:213], v[100:103]
	v_mfma_f32_16x16x32_bf16 v[96:99], v[168:171], v[210:213], v[96:99]
	v_mfma_f32_16x16x32_bf16 v[84:87], v[154:157], v[218:221], v[84:87]
	v_mfma_f32_16x16x32_bf16 v[80:83], v[168:171], v[218:221], v[80:83]
	v_mfma_f32_16x16x32_bf16 v[132:135], v[158:161], v[180:183], v[132:135]
	v_mfma_f32_16x16x32_bf16 v[128:131], v[172:175], v[180:183], v[128:131]
	v_mfma_f32_16x16x32_bf16 v[116:119], v[158:161], v[188:191], v[116:119]
	v_mfma_f32_16x16x32_bf16 v[112:115], v[172:175], v[188:191], v[112:115]
	v_mfma_f32_16x16x32_bf16 v[100:103], v[158:161], v[214:217], v[100:103]
	v_mfma_f32_16x16x32_bf16 v[96:99], v[172:175], v[214:217], v[96:99]
	v_mfma_f32_16x16x32_bf16 v[84:87], v[158:161], v[222:225], v[84:87]
	v_mfma_f32_16x16x32_bf16 v[80:83], v[172:175], v[222:225], v[80:83]
	s_setprio 0
	s_barrier
; #define PG8_STAGE(bufoff, gbase, voff) do { _Pragma("unroll") for (int _i = 0; _i < 2; ++_i) _Pragma("unroll") for (int _r = 0; _r < PG8_NREP; ++_r) \
;         __builtin_amdgcn_global_load_lds((const unsigned*)((const char*)(gbase) + (voff)[_i]), (PG8_LAS unsigned*)(lds + (bufoff) + ldsw + _i * 8192), 16, 0, 0); } while (0)
; #define PG8_LDA(dst, b, h) do { _Pragma("unroll") for (int m = 0; m < 4; ++m) _Pragma("unroll") for (int k = 0; k < 2; ++k) { dst[m][k] = *(const PG8_LAS bf16x8*)(lds + PG8_SA(b, h) + aoff + m * 2048 + k * 1024); PG8_DUP((unsigned)(uintptr_t)(lds + PG8_SA(b, h) + aoff + m * 2048 + k * 1024)); } } while (0)
; #define PG8_MMA(ai, bj, At, Bt) do { __builtin_amdgcn_s_setprio(1); _Pragma("unroll") for (int m = 0; m < 4; ++m) _Pragma("unroll") for (int n = 0; n < 2; ++n) _Pragma("unroll") for (int k = 0; k < 2; ++k) \
;         acc[ai][bj][m][n] = __builtin_amdgcn_mfma_f32_16x16x32_bf16(Bt[n][k], At[m][k], acc[ai][bj][m][n], 0, 0, 0); __builtin_amdgcn_s_setprio(0); } while (0)
; #define PG8_WAIT_V(n) do { if ((n) == 0) asm volatile("s_waitcnt vmcnt(0)" ::: "memory"); else if ((n) == 2) asm volatile("s_waitcnt vmcnt(4)" ::: "memory"); else if ((n) == 4) asm volatile("s_waitcnt vmcnt(8)" ::: "memory"); \
;     else if ((n) == 6) asm volatile("s_waitcnt vmcnt(12)" ::: "memory"); else asm volatile("s_waitcnt vmcnt(16)" ::: "memory"); } while (0)
; #define PG8_WAIT_V(n) asm volatile("s_waitcnt vmcnt(" #n ")" ::: "memory")
; #define PG8_WAIT_L(n) asm volatile("s_waitcnt lgkmcnt(" #n ")" ::: "memory")
; #define PG8_BAR __builtin_amdgcn_s_barrier()
; #define PG8_SCHED __builtin_amdgcn_sched_barrier(0)
; template <class Epi, class Sched, bool ALIGN_EPI = false, bool SP2 = false>
; __device__ __forceinline__ void gemm_phase(PG8_LAS unsigned char* lds, const Gemm g, const Sched& S, const Epi& E) {
;     ...
;             PG8_LDA(At, 1, 1); PG8_STAGE(PG8_SB(1, 0), b3, voffB); PG8_STAGE(PG8_SB(1, 1), b3 + hstepB, voffB); PG8_STAGE(PG8_SA(1, 0), a3, voffA);
;             PG8_WAIT_V(8); PG8_WAIT_L(0); PG8_BAR; PG8_MMA(1, 0, At, B0); PG8_MMA(1, 1, At, B1); PG8_BAR; PG8_SCHED;
;     ...
;         if constexpr (ALIGN_EPI) { if (wr == 0) PG8_BAR; }
	s_add_i32 s26, s28, s86
	v_lshl_add_u64 v[162:163], v[162:163], 0, s[68:69]
	s_mov_b32 m0, s26
	ds_read_b128 v[176:179], v167 offset:49152
	ds_read_b128 v[180:183], v167 offset:50176
	ds_read_b128 v[184:187], v167 offset:51200
	ds_read_b128 v[188:191], v167 offset:52224
	ds_read_b128 v[210:213], v167 offset:53248
	ds_read_b128 v[214:217], v167 offset:54272
	ds_read_b128 v[218:221], v167 offset:55296
	ds_read_b128 v[222:225], v167 offset:56320
	global_load_lds_dwordx4 v[162:163], off
	s_add_i32 m0, s26, 0x2000
	s_add_u32 s26, s92, 0x80080
	v_lshl_add_u64 v[162:163], v[194:195], 0, s[68:69]
	s_addc_u32 s27, s93, 0
	s_add_i32 s28, s29, s86
	global_load_lds_dwordx4 v[162:163], off
	v_lshl_add_u64 v[162:163], s[26:27], 0, v[192:193]
	s_mov_b32 m0, s28
	s_nop 0
	global_load_lds_dwordx4 v[162:163], off
	v_lshl_add_u64 v[162:163], s[26:27], 0, v[144:145]
	s_add_i32 m0, s28, 0x2000
	s_nop 0
	global_load_lds_dwordx4 v[162:163], off
	v_lshl_add_u64 v[162:163], v[196:197], 0, s[68:69]
	s_mov_b32 m0, s18
	s_nop 0
	global_load_lds_dwordx4 v[162:163], off
	v_lshl_add_u64 v[162:163], v[200:201], 0, s[68:69]
	s_mov_b32 m0, s19
	s_nop 0
	global_load_lds_dwordx4 v[162:163], off
	s_waitcnt vmcnt(8)
	s_waitcnt lgkmcnt(0)
	s_barrier
	s_setprio 1
	s_waitcnt lgkmcnt(0)
	v_mfma_f32_16x16x32_bf16 v[76:79], v[48:51], v[176:179], v[76:79]
	v_mfma_f32_16x16x32_bf16 v[72:75], v[64:67], v[176:179], v[72:75]
	v_mfma_f32_16x16x32_bf16 v[60:63], v[48:51], v[184:187], v[60:63]
	v_mfma_f32_16x16x32_bf16 v[56:59], v[64:67], v[184:187], v[56:59]
	v_mfma_f32_16x16x32_bf16 v[36:39], v[48:51], v[210:213], v[36:39]
	v_mfma_f32_16x16x32_bf16 v[32:35], v[64:67], v[210:213], v[32:35]
	v_mfma_f32_16x16x32_bf16 v[12:15], v[48:51], v[218:221], v[12:15]
	v_mfma_f32_16x16x32_bf16 v[8:11], v[64:67], v[218:221], v[8:11]
	v_mfma_f32_16x16x32_bf16 v[76:79], v[52:55], v[180:183], v[76:79]
	v_mfma_f32_16x16x32_bf16 v[72:75], v[68:71], v[180:183], v[72:75]
	v_mfma_f32_16x16x32_bf16 v[60:63], v[52:55], v[188:191], v[60:63]
	v_mfma_f32_16x16x32_bf16 v[56:59], v[68:71], v[188:191], v[56:59]
	v_mfma_f32_16x16x32_bf16 v[36:39], v[52:55], v[214:217], v[36:39]
	v_mfma_f32_16x16x32_bf16 v[32:35], v[68:71], v[214:217], v[32:35]
	v_mfma_f32_16x16x32_bf16 v[12:15], v[52:55], v[222:225], v[12:15]
	v_mfma_f32_16x16x32_bf16 v[8:11], v[68:71], v[222:225], v[8:11]
	s_setprio 0
	s_setprio 1
	v_mfma_f32_16x16x32_bf16 v[24:27], v[154:157], v[176:179], v[24:27]
	v_mfma_f32_16x16x32_bf16 v[68:71], v[158:161], v[180:183], v[24:27]
	v_mfma_f32_16x16x32_bf16 v[24:27], v[168:171], v[176:179], v[28:31]
	v_mfma_f32_16x16x32_bf16 v[64:67], v[172:175], v[180:183], v[24:27]
	v_mfma_f32_16x16x32_bf16 v[24:27], v[154:157], v[184:187], v[44:47]
	v_mfma_f32_16x16x32_bf16 v[44:47], v[158:161], v[188:191], v[24:27]
	v_mfma_f32_16x16x32_bf16 v[24:27], v[168:171], v[184:187], v[40:43]
	v_mfma_f32_16x16x32_bf16 v[20:23], v[154:157], v[210:213], v[20:23]
	v_mfma_f32_16x16x32_bf16 v[16:19], v[168:171], v[210:213], v[16:19]
	v_mfma_f32_16x16x32_bf16 v[4:7], v[154:157], v[218:221], v[4:7]
	v_mfma_f32_16x16x32_bf16 v[0:3], v[168:171], v[218:221], v[0:3]
	v_mfma_f32_16x16x32_bf16 v[40:43], v[172:175], v[188:191], v[24:27]
	v_mfma_f32_16x16x32_bf16 v[20:23], v[158:161], v[214:217], v[20:23]
	v_mfma_f32_16x16x32_bf16 v[16:19], v[172:175], v[214:217], v[16:19]
	v_mfma_f32_16x16x32_bf16 v[4:7], v[158:161], v[222:225], v[4:7]
	v_mfma_f32_16x16x32_bf16 v[0:3], v[172:175], v[222:225], v[0:3]
	s_setprio 0
	s_add_i32 s25, s25, 2
	s_add_u32 s14, s14, 0x100
	s_addc_u32 s15, s15, 0
	s_add_u32 vcc_hi, vcc_hi, 0x100
	s_addc_u32 s24, s24, 0
	s_cmp_gt_u32 s25, 29
	s_barrier
	s_cbranch_scc0 .LBB0_684
	s_and_b64 vcc, exec, s[52:53]
	s_cbranch_vccz .LBB0_687
	s_barrier

; #define PG8_STAGE(bufoff, gbase, voff) do { _Pragma("unroll") for (int _i = 0; _i < 2; ++_i) _Pragma("unroll") for (int _r = 0; _r < PG8_NREP; ++_r) \
;         __builtin_amdgcn_global_load_lds((const unsigned*)((const char*)(gbase) + (voff)[_i]), (PG8_LAS unsigned*)(lds + (bufoff) + ldsw + _i * 8192), 16, 0, 0); } while (0)
; #define PG8_LDA(dst, b, h) do { _Pragma("unroll") for (int m = 0; m < 4; ++m) _Pragma("unroll") for (int k = 0; k < 2; ++k) { dst[m][k] = *(const PG8_LAS bf16x8*)(lds + PG8_SA(b, h) + aoff + m * 2048 + k * 1024); PG8_DUP((unsigned)(uintptr_t)(lds + PG8_SA(b, h) + aoff + m * 2048 + k * 1024)); } } while (0)
; #define PG8_LDB(dst, b, h) do { _Pragma("unroll") for (int n = 0; n < 2; ++n) _Pragma("unroll") for (int k = 0; k < 2; ++k) { dst[n][k] = *(const PG8_LAS bf16x8*)(lds + PG8_SB(b, h) + boff + n * 2048 + k * 1024); PG8_DUP((unsigned)(uintptr_t)(lds + PG8_SB(b, h) + boff + n * 2048 + k * 1024)); } } while (0)
; #define PG8_MMA(ai, bj, At, Bt) do { __builtin_amdgcn_s_setprio(1); _Pragma("unroll") for (int m = 0; m < 4; ++m) _Pragma("unroll") for (int n = 0; n < 2; ++n) _Pragma("unroll") for (int k = 0; k < 2; ++k) \
;         acc[ai][bj][m][n] = __builtin_amdgcn_mfma_f32_16x16x32_bf16(Bt[n][k], At[m][k], acc[ai][bj][m][n], 0, 0, 0); __builtin_amdgcn_s_setprio(0); } while (0)
; template <class Epi, class Sched, bool ALIGN_EPI = false, bool SP2 = false>
; __device__ __forceinline__ void gemm_phase(PG8_LAS unsigned char* lds, const Gemm g, const Sched& S, const Epi& E) {
;     ...
;             const bool last = (t == nt - 2);
;             const char* a1 = cA + (size_t)(t + 1) * kstep;
;             const char* a2 = last ? nA : cA + (size_t)(t + 2) * kstep; const char* b2 = last ? nB : cB + (size_t)(t + 2) * kstep;
;             const char* a3 = a2 + kstep; const char* b3 = b2 + kstep;
;             if (last && has_next) S.a_ready(nxt);
;             if constexpr (SP2) {
;     ...
;             if (Epi::PERM && sizeof(Epi) && TEST_DRAIN) PG8_WAIT_V(0);
;     ...
;             PG8_LDB(B0, 0, 0); PG8_LDB(B1, 0, 1); PG8_SCHED; PG8_LDA(At, 0, 0); PG8_STAGE(PG8_SA(1, 1), a1 + hstepA, voffA);
;             PG8_WAIT_V(8); PG8_WAIT_L(0); PG8_BAR; PG8_MMA(0, 0, At, B0); PG8_MMA(0, 1, At, B1); PG8_BAR; PG8_SCHED;
;             PG8_LDA(At, 0, 1); PG8_STAGE(PG8_SB(0, 0), b2, voffB); PG8_STAGE(PG8_SB(0, 1), b2 + hstepB, voffB); PG8_STAGE(PG8_SA(0, 0), a2, voffA);
.LBB0_772:
	s_add_u32 s26, s52, 0xfff80080
	s_addc_u32 s27, s53, -1
	s_add_i32 s28, 0, 0x10000
	s_cmp_eq_u32 s25, 28
	s_cselect_b32 s59, s47, s27
	s_cselect_b32 s58, s86, s26
	v_add_u32_e32 v142, s28, v145
	s_cselect_b32 s55, s45, s24
	s_cselect_b32 s54, s91, s92
	s_add_i32 s29, 0, 0x14000
	ds_read_b128 v[138:141], v142
	ds_read_b128 v[148:151], v142 offset:1024
	ds_read_b128 v[152:155], v142 offset:2048
	ds_read_b128 v[156:159], v142 offset:3072
	v_add_u32_e32 v142, s29, v145
	ds_read_b128 v[160:163], v142
	ds_read_b128 v[164:167], v142 offset:1024
	ds_read_b128 v[168:171], v142 offset:2048
	ds_read_b128 v[172:175], v142 offset:3072
	v_lshl_add_u64 v[142:143], s[52:53], 0, v[134:135]
	s_add_i32 m0, s17, 0xc000
	ds_read_b128 v[176:179], v147
	ds_read_b128 v[180:183], v147 offset:1024
	ds_read_b128 v[184:187], v147 offset:2048
	ds_read_b128 v[188:191], v147 offset:3072
	ds_read_b128 v[194:197], v147 offset:4096
	ds_read_b128 v[210:213], v147 offset:5120
	ds_read_b128 v[214:217], v147 offset:6144
	ds_read_b128 v[218:221], v147 offset:7168
	global_load_lds_dwordx4 v[142:143], off
	v_lshl_add_u64 v[142:143], s[52:53], 0, v[136:137]
	s_add_i32 m0, s17, 0xe000
	s_nop 0
	global_load_lds_dwordx4 v[142:143], off
	s_waitcnt vmcnt(8)
	s_waitcnt lgkmcnt(0)
	s_barrier
	s_setprio 1
	s_waitcnt lgkmcnt(0)
	v_mfma_f32_16x16x32_bf16 v[124:127], v[138:141], v[176:179], v[124:127]
	v_mfma_f32_16x16x32_bf16 v[120:123], v[152:155], v[176:179], v[120:123]
	v_mfma_f32_16x16x32_bf16 v[108:111], v[138:141], v[184:187], v[108:111]
	v_mfma_f32_16x16x32_bf16 v[104:107], v[152:155], v[184:187], v[104:107]
	v_mfma_f32_16x16x32_bf16 v[92:95], v[138:141], v[194:197], v[92:95]
	v_mfma_f32_16x16x32_bf16 v[88:91], v[152:155], v[194:197], v[88:91]
	v_mfma_f32_16x16x32_bf16 v[76:79], v[138:141], v[214:217], v[76:79]
	v_mfma_f32_16x16x32_bf16 v[72:75], v[152:155], v[214:217], v[72:75]
	v_mfma_f32_16x16x32_bf16 v[124:127], v[148:151], v[180:183], v[124:127]
	v_mfma_f32_16x16x32_bf16 v[120:123], v[156:159], v[180:183], v[120:123]
	v_mfma_f32_16x16x32_bf16 v[108:111], v[148:151], v[188:191], v[108:111]
	v_mfma_f32_16x16x32_bf16 v[104:107], v[156:159], v[188:191], v[104:107]
	v_mfma_f32_16x16x32_bf16 v[92:95], v[148:151], v[210:213], v[92:95]
	v_mfma_f32_16x16x32_bf16 v[88:91], v[156:159], v[210:213], v[88:91]
	v_mfma_f32_16x16x32_bf16 v[76:79], v[148:151], v[218:221], v[76:79]
	v_mfma_f32_16x16x32_bf16 v[72:75], v[156:159], v[218:221], v[72:75]
	s_setprio 0
	s_setprio 1
	v_mfma_f32_16x16x32_bf16 v[116:119], v[160:163], v[176:179], v[116:119]
	v_mfma_f32_16x16x32_bf16 v[112:115], v[168:171], v[176:179], v[112:115]
	v_mfma_f32_16x16x32_bf16 v[100:103], v[160:163], v[184:187], v[100:103]
	v_mfma_f32_16x16x32_bf16 v[96:99], v[168:171], v[184:187], v[96:99]
	v_mfma_f32_16x16x32_bf16 v[84:87], v[160:163], v[194:197], v[84:87]
	v_mfma_f32_16x16x32_bf16 v[80:83], v[168:171], v[194:197], v[80:83]
	v_mfma_f32_16x16x32_bf16 v[68:71], v[160:163], v[214:217], v[68:71]
	v_mfma_f32_16x16x32_bf16 v[64:67], v[168:171], v[214:217], v[64:67]
	v_mfma_f32_16x16x32_bf16 v[116:119], v[164:167], v[180:183], v[116:119]
	v_mfma_f32_16x16x32_bf16 v[112:115], v[172:175], v[180:183], v[112:115]
	v_mfma_f32_16x16x32_bf16 v[100:103], v[164:167], v[188:191], v[100:103]
	v_mfma_f32_16x16x32_bf16 v[96:99], v[172:175], v[188:191], v[96:99]
	v_mfma_f32_16x16x32_bf16 v[84:87], v[164:167], v[210:213], v[84:87]
	v_mfma_f32_16x16x32_bf16 v[80:83], v[172:175], v[210:213], v[80:83]
	v_mfma_f32_16x16x32_bf16 v[68:71], v[164:167], v[218:221], v[68:71]
	v_mfma_f32_16x16x32_bf16 v[64:67], v[172:175], v[218:221], v[64:67]
	s_setprio 0
	s_barrier
	s_add_i32 s26, s28, s16
	v_lshl_add_u64 v[142:143], s[54:55], 0, v[192:193]
	s_mov_b32 m0, s26
	ds_read_b128 v[176:179], v147 offset:16384
	ds_read_b128 v[180:183], v147 offset:17408
	ds_read_b128 v[184:187], v147 offset:18432
	ds_read_b128 v[188:191], v147 offset:19456
	ds_read_b128 v[194:197], v147 offset:20480
	ds_read_b128 v[210:213], v147 offset:21504
	ds_read_b128 v[214:217], v147 offset:22528
	ds_read_b128 v[218:221], v147 offset:23552
	global_load_lds_dwordx4 v[142:143], off
	s_add_i32 m0, s26, 0x2000
	s_add_u32 s26, s54, 0x80000
	v_lshl_add_u64 v[200:201], s[54:55], 0, v[128:129]
	s_addc_u32 s27, s55, 0
	s_add_i32 s28, s29, s16
	global_load_lds_dwordx4 v[200:201], off
	v_lshl_add_u64 v[222:223], s[26:27], 0, v[192:193]
	s_mov_b32 m0, s28
	v_lshl_add_u64 v[224:225], s[58:59], 0, v[130:131]
	global_load_lds_dwordx4 v[222:223], off
	v_lshl_add_u64 v[222:223], s[26:27], 0, v[128:129]
	s_add_i32 m0, s28, 0x2000
	s_nop 0
	global_load_lds_dwordx4 v[222:223], off
	v_lshl_add_u64 v[222:223], s[58:59], 0, v[132:133]
	s_mov_b32 m0, s17
	s_nop 0
	global_load_lds_dwordx4 v[222:223], off
	s_mov_b32 m0, s18
	s_nop 0
	global_load_lds_dwordx4 v[224:225], off
	s_waitcnt vmcnt(8)
	s_waitcnt lgkmcnt(0)
	s_barrier
; #define PG8_STAGE(bufoff, gbase, voff) do { _Pragma("unroll") for (int _i = 0; _i < 2; ++_i) _Pragma("unroll") for (int _r = 0; _r < PG8_NREP; ++_r) \
;         __builtin_amdgcn_global_load_lds((const unsigned*)((const char*)(gbase) + (voff)[_i]), (PG8_LAS unsigned*)(lds + (bufoff) + ldsw + _i * 8192), 16, 0, 0); } while (0)
; #define PG8_LDA(dst, b, h) do { _Pragma("unroll") for (int m = 0; m < 4; ++m) _Pragma("unroll") for (int k = 0; k < 2; ++k) { dst[m][k] = *(const PG8_LAS bf16x8*)(lds + PG8_SA(b, h) + aoff + m * 2048 + k * 1024); PG8_DUP((unsigned)(uintptr_t)(lds + PG8_SA(b, h) + aoff + m * 2048 + k * 1024)); } } while (0)
; #define PG8_LDB(dst, b, h) do { _Pragma("unroll") for (int n = 0; n < 2; ++n) _Pragma("unroll") for (int k = 0; k < 2; ++k) { dst[n][k] = *(const PG8_LAS bf16x8*)(lds + PG8_SB(b, h) + boff + n * 2048 + k * 1024); PG8_DUP((unsigned)(uintptr_t)(lds + PG8_SB(b, h) + boff + n * 2048 + k * 1024)); } } while (0)
; #define PG8_MMA(ai, bj, At, Bt) do { __builtin_amdgcn_s_setprio(1); _Pragma("unroll") for (int m = 0; m < 4; ++m) _Pragma("unroll") for (int n = 0; n < 2; ++n) _Pragma("unroll") for (int k = 0; k < 2; ++k) \
;         acc[ai][bj][m][n] = __builtin_amdgcn_mfma_f32_16x16x32_bf16(Bt[n][k], At[m][k], acc[ai][bj][m][n], 0, 0, 0); __builtin_amdgcn_s_setprio(0); } while (0)
; #define PG8_WAIT_V(n) do { if ((n) == 0) asm volatile("s_waitcnt vmcnt(0)" ::: "memory"); else if ((n) == 2) asm volatile("s_waitcnt vmcnt(4)" ::: "memory"); else if ((n) == 4) asm volatile("s_waitcnt vmcnt(8)" ::: "memory"); \
;     else if ((n) == 6) asm volatile("s_waitcnt vmcnt(12)" ::: "memory"); else asm volatile("s_waitcnt vmcnt(16)" ::: "memory"); } while (0)
; #define PG8_WAIT_V(n) asm volatile("s_waitcnt vmcnt(" #n ")" ::: "memory")
; #define PG8_BAR __builtin_amdgcn_s_barrier()
; template <class Epi, class Sched, bool ALIGN_EPI = false, bool SP2 = false>
; __device__ __forceinline__ void gemm_phase(PG8_LAS unsigned char* lds, const Gemm g, const Sched& S, const Epi& E) {
;     ...
;             PG8_WAIT_V(8); PG8_WAIT_L(0); PG8_BAR; PG8_MMA(1, 0, At, B0); PG8_MMA(1, 1, At, B1); PG8_BAR; PG8_SCHED;
;             PG8_LDB(B0, 1, 0); PG8_LDB(B1, 1, 1); PG8_SCHED; PG8_LDA(At, 1, 0); PG8_STAGE(PG8_SA(0, 1), a2 + hstepA, voffA);
;             PG8_WAIT_V(8); PG8_WAIT_L(0); PG8_BAR; PG8_MMA(0, 0, At, B0); PG8_MMA(0, 1, At, B1); PG8_BAR; PG8_SCHED;
	s_setprio 1
	s_waitcnt lgkmcnt(0)
	v_mfma_f32_16x16x32_bf16 v[60:63], v[138:141], v[176:179], v[60:63]
	v_mfma_f32_16x16x32_bf16 v[56:59], v[152:155], v[176:179], v[56:59]
	v_mfma_f32_16x16x32_bf16 v[44:47], v[138:141], v[184:187], v[44:47]
	v_mfma_f32_16x16x32_bf16 v[40:43], v[152:155], v[184:187], v[40:43]
	v_mfma_f32_16x16x32_bf16 v[28:31], v[138:141], v[194:197], v[28:31]
	v_mfma_f32_16x16x32_bf16 v[24:27], v[152:155], v[194:197], v[24:27]
	v_mfma_f32_16x16x32_bf16 v[12:15], v[138:141], v[214:217], v[12:15]
	v_mfma_f32_16x16x32_bf16 v[8:11], v[152:155], v[214:217], v[8:11]
	v_mfma_f32_16x16x32_bf16 v[60:63], v[148:151], v[180:183], v[60:63]
	v_mfma_f32_16x16x32_bf16 v[56:59], v[156:159], v[180:183], v[56:59]
	v_mfma_f32_16x16x32_bf16 v[44:47], v[148:151], v[188:191], v[44:47]
	v_mfma_f32_16x16x32_bf16 v[40:43], v[156:159], v[188:191], v[40:43]
	v_mfma_f32_16x16x32_bf16 v[28:31], v[148:151], v[210:213], v[28:31]
	v_mfma_f32_16x16x32_bf16 v[24:27], v[156:159], v[210:213], v[24:27]
	v_mfma_f32_16x16x32_bf16 v[12:15], v[148:151], v[218:221], v[12:15]
	v_mfma_f32_16x16x32_bf16 v[8:11], v[156:159], v[218:221], v[8:11]
	s_setprio 0
	s_setprio 1
	v_mfma_f32_16x16x32_bf16 v[52:55], v[160:163], v[176:179], v[52:55]
	v_mfma_f32_16x16x32_bf16 v[48:51], v[168:171], v[176:179], v[48:51]
	v_mfma_f32_16x16x32_bf16 v[36:39], v[160:163], v[184:187], v[36:39]
	v_mfma_f32_16x16x32_bf16 v[32:35], v[168:171], v[184:187], v[32:35]
	v_mfma_f32_16x16x32_bf16 v[20:23], v[160:163], v[194:197], v[20:23]
	v_mfma_f32_16x16x32_bf16 v[16:19], v[168:171], v[194:197], v[16:19]
	v_mfma_f32_16x16x32_bf16 v[4:7], v[160:163], v[214:217], v[4:7]
	v_mfma_f32_16x16x32_bf16 v[0:3], v[168:171], v[214:217], v[0:3]
	v_mfma_f32_16x16x32_bf16 v[52:55], v[164:167], v[180:183], v[52:55]
	v_mfma_f32_16x16x32_bf16 v[48:51], v[172:175], v[180:183], v[48:51]
	v_mfma_f32_16x16x32_bf16 v[36:39], v[164:167], v[188:191], v[36:39]
	v_mfma_f32_16x16x32_bf16 v[32:35], v[172:175], v[188:191], v[32:35]
	v_mfma_f32_16x16x32_bf16 v[20:23], v[164:167], v[210:213], v[20:23]
	v_mfma_f32_16x16x32_bf16 v[16:19], v[172:175], v[210:213], v[16:19]
	v_mfma_f32_16x16x32_bf16 v[4:7], v[164:167], v[218:221], v[4:7]
	v_mfma_f32_16x16x32_bf16 v[0:3], v[172:175], v[218:221], v[0:3]
	s_setprio 0
	s_barrier
	s_add_i32 s28, 0, 0x18000
	s_add_i32 s29, 0, 0x1c000
	v_add_u32_e32 v156, s28, v145
	v_add_u32_e32 v172, s29, v145
	ds_read_b128 v[138:141], v156
	ds_read_b128 v[148:151], v156 offset:1024
	ds_read_b128 v[152:155], v156 offset:2048
	ds_read_b128 v[156:159], v156 offset:3072
	ds_read_b128 v[160:163], v172
	ds_read_b128 v[164:167], v172 offset:1024
	ds_read_b128 v[168:171], v172 offset:2048
	ds_read_b128 v[172:175], v172 offset:3072
	s_add_u32 s26, s58, 0x80000
	s_addc_u32 s27, s59, 0
	s_mov_b32 m0, s19
	v_lshl_add_u64 v[226:227], s[26:27], 0, v[132:133]
	ds_read_b128 v[176:179], v147 offset:32768
	ds_read_b128 v[180:183], v147 offset:33792
	ds_read_b128 v[184:187], v147 offset:34816
	ds_read_b128 v[188:191], v147 offset:35840
	ds_read_b128 v[194:197], v147 offset:36864
	ds_read_b128 v[210:213], v147 offset:37888
	ds_read_b128 v[214:217], v147 offset:38912
	ds_read_b128 v[218:221], v147 offset:39936
	global_load_lds_dwordx4 v[226:227], off
	v_lshl_add_u64 v[226:227], s[26:27], 0, v[130:131]
	s_mov_b32 m0, s20
	s_nop 0
	global_load_lds_dwordx4 v[226:227], off
	s_waitcnt vmcnt(8)
	s_waitcnt lgkmcnt(0)
	s_barrier
	s_setprio 1
	s_waitcnt lgkmcnt(0)
	v_mfma_f32_16x16x32_bf16 v[124:127], v[138:141], v[176:179], v[124:127]
	v_mfma_f32_16x16x32_bf16 v[120:123], v[152:155], v[176:179], v[120:123]
	v_mfma_f32_16x16x32_bf16 v[108:111], v[138:141], v[184:187], v[108:111]
	v_mfma_f32_16x16x32_bf16 v[104:107], v[152:155], v[184:187], v[104:107]
	v_mfma_f32_16x16x32_bf16 v[92:95], v[138:141], v[194:197], v[92:95]
	v_mfma_f32_16x16x32_bf16 v[88:91], v[152:155], v[194:197], v[88:91]
	v_mfma_f32_16x16x32_bf16 v[76:79], v[138:141], v[214:217], v[76:79]
	v_mfma_f32_16x16x32_bf16 v[72:75], v[152:155], v[214:217], v[72:75]
	v_mfma_f32_16x16x32_bf16 v[124:127], v[148:151], v[180:183], v[124:127]
	v_mfma_f32_16x16x32_bf16 v[120:123], v[156:159], v[180:183], v[120:123]
	v_mfma_f32_16x16x32_bf16 v[108:111], v[148:151], v[188:191], v[108:111]
	v_mfma_f32_16x16x32_bf16 v[104:107], v[156:159], v[188:191], v[104:107]
	v_mfma_f32_16x16x32_bf16 v[92:95], v[148:151], v[210:213], v[92:95]
	v_mfma_f32_16x16x32_bf16 v[88:91], v[156:159], v[210:213], v[88:91]
	v_mfma_f32_16x16x32_bf16 v[76:79], v[148:151], v[218:221], v[76:79]
	v_mfma_f32_16x16x32_bf16 v[72:75], v[156:159], v[218:221], v[72:75]
	s_setprio 0
	s_setprio 1
	v_mfma_f32_16x16x32_bf16 v[116:119], v[160:163], v[176:179], v[116:119]
	v_mfma_f32_16x16x32_bf16 v[112:115], v[168:171], v[176:179], v[112:115]
	v_mfma_f32_16x16x32_bf16 v[100:103], v[160:163], v[184:187], v[100:103]
	v_mfma_f32_16x16x32_bf16 v[96:99], v[168:171], v[184:187], v[96:99]
	v_mfma_f32_16x16x32_bf16 v[84:87], v[160:163], v[194:197], v[84:87]
	v_mfma_f32_16x16x32_bf16 v[80:83], v[168:171], v[194:197], v[80:83]
	v_mfma_f32_16x16x32_bf16 v[68:71], v[160:163], v[214:217], v[68:71]
	v_mfma_f32_16x16x32_bf16 v[64:67], v[168:171], v[214:217], v[64:67]
	v_mfma_f32_16x16x32_bf16 v[116:119], v[164:167], v[180:183], v[116:119]
	v_mfma_f32_16x16x32_bf16 v[112:115], v[172:175], v[180:183], v[112:115]
	v_mfma_f32_16x16x32_bf16 v[100:103], v[164:167], v[188:191], v[100:103]
	v_mfma_f32_16x16x32_bf16 v[96:99], v[172:175], v[188:191], v[96:99]
	v_mfma_f32_16x16x32_bf16 v[84:87], v[164:167], v[210:213], v[84:87]
	v_mfma_f32_16x16x32_bf16 v[80:83], v[172:175], v[210:213], v[80:83]
	v_mfma_f32_16x16x32_bf16 v[68:71], v[164:167], v[218:221], v[68:71]
	v_mfma_f32_16x16x32_bf16 v[64:67], v[172:175], v[218:221], v[64:67]
	s_setprio 0
	s_barrier
; #define PG8_STAGE(bufoff, gbase, voff) do { _Pragma("unroll") for (int _i = 0; _i < 2; ++_i) _Pragma("unroll") for (int _r = 0; _r < PG8_NREP; ++_r) \
;         __builtin_amdgcn_global_load_lds((const unsigned*)((const char*)(gbase) + (voff)[_i]), (PG8_LAS unsigned*)(lds + (bufoff) + ldsw + _i * 8192), 16, 0, 0); } while (0)
; #define PG8_LDA(dst, b, h) do { _Pragma("unroll") for (int m = 0; m < 4; ++m) _Pragma("unroll") for (int k = 0; k < 2; ++k) { dst[m][k] = *(const PG8_LAS bf16x8*)(lds + PG8_SA(b, h) + aoff + m * 2048 + k * 1024); PG8_DUP((unsigned)(uintptr_t)(lds + PG8_SA(b, h) + aoff + m * 2048 + k * 1024)); } } while (0)
; #define PG8_MMA(ai, bj, At, Bt) do { __builtin_amdgcn_s_setprio(1); _Pragma("unroll") for (int m = 0; m < 4; ++m) _Pragma("unroll") for (int n = 0; n < 2; ++n) _Pragma("unroll") for (int k = 0; k < 2; ++k) \
;         acc[ai][bj][m][n] = __builtin_amdgcn_mfma_f32_16x16x32_bf16(Bt[n][k], At[m][k], acc[ai][bj][m][n], 0, 0, 0); __builtin_amdgcn_s_setprio(0); } while (0)
; #define PG8_WAIT_V(n) do { if ((n) == 0) asm volatile("s_waitcnt vmcnt(0)" ::: "memory"); else if ((n) == 2) asm volatile("s_waitcnt vmcnt(4)" ::: "memory"); else if ((n) == 4) asm volatile("s_waitcnt vmcnt(8)" ::: "memory"); \
;     else if ((n) == 6) asm volatile("s_waitcnt vmcnt(12)" ::: "memory"); else asm volatile("s_waitcnt vmcnt(16)" ::: "memory"); } while (0)
; #define PG8_WAIT_V(n) asm volatile("s_waitcnt vmcnt(" #n ")" ::: "memory")
; #define PG8_WAIT_L(n) asm volatile("s_waitcnt lgkmcnt(" #n ")" ::: "memory")
; #define PG8_BAR __builtin_amdgcn_s_barrier()
; #define PG8_SCHED __builtin_amdgcn_sched_barrier(0)
; template <class Epi, class Sched, bool ALIGN_EPI = false, bool SP2 = false>
; __device__ __forceinline__ void gemm_phase(PG8_LAS unsigned char* lds, const Gemm g, const Sched& S, const Epi& E) {
;     ...
;             PG8_LDA(At, 1, 1); PG8_STAGE(PG8_SB(1, 0), b3, voffB); PG8_STAGE(PG8_SB(1, 1), b3 + hstepB, voffB); PG8_STAGE(PG8_SA(1, 0), a3, voffA);
;             PG8_WAIT_V(8); PG8_WAIT_L(0); PG8_BAR; PG8_MMA(1, 0, At, B0); PG8_MMA(1, 1, At, B1); PG8_BAR; PG8_SCHED;
;     ...
;         if constexpr (ALIGN_EPI) { if (wr == 0) PG8_BAR; }
	s_add_i32 s26, s28, s16
	v_lshl_add_u64 v[142:143], v[142:143], 0, s[68:69]
	s_mov_b32 m0, s26
	ds_read_b128 v[176:179], v147 offset:49152
	ds_read_b128 v[180:183], v147 offset:50176
	ds_read_b128 v[184:187], v147 offset:51200
	ds_read_b128 v[188:191], v147 offset:52224
	ds_read_b128 v[194:197], v147 offset:53248
	ds_read_b128 v[210:213], v147 offset:54272
	ds_read_b128 v[214:217], v147 offset:55296
	ds_read_b128 v[218:221], v147 offset:56320
	global_load_lds_dwordx4 v[142:143], off
	s_add_i32 m0, s26, 0x2000
	s_add_u32 s26, s54, 0x80080
	v_lshl_add_u64 v[142:143], v[200:201], 0, s[68:69]
	s_addc_u32 s27, s55, 0
	s_add_i32 s28, s29, s16
	global_load_lds_dwordx4 v[142:143], off
	v_lshl_add_u64 v[142:143], s[26:27], 0, v[192:193]
	s_mov_b32 m0, s28
	s_nop 0
	global_load_lds_dwordx4 v[142:143], off
	v_lshl_add_u64 v[142:143], s[26:27], 0, v[128:129]
	s_add_i32 m0, s28, 0x2000
	s_nop 0
	global_load_lds_dwordx4 v[142:143], off
	v_lshl_add_u64 v[142:143], v[222:223], 0, s[68:69]
	s_mov_b32 m0, s21
	s_nop 0
	global_load_lds_dwordx4 v[142:143], off
	v_lshl_add_u64 v[142:143], v[224:225], 0, s[68:69]
	s_mov_b32 m0, s22
	s_nop 0
	global_load_lds_dwordx4 v[142:143], off
	s_waitcnt vmcnt(8)
	s_waitcnt lgkmcnt(0)
	s_barrier
	s_setprio 1
	s_waitcnt lgkmcnt(0)
	v_mfma_f32_16x16x32_bf16 v[60:63], v[138:141], v[176:179], v[60:63]
	v_mfma_f32_16x16x32_bf16 v[56:59], v[152:155], v[176:179], v[56:59]
	v_mfma_f32_16x16x32_bf16 v[44:47], v[138:141], v[184:187], v[44:47]
	v_mfma_f32_16x16x32_bf16 v[40:43], v[152:155], v[184:187], v[40:43]
	v_mfma_f32_16x16x32_bf16 v[28:31], v[138:141], v[194:197], v[28:31]
	v_mfma_f32_16x16x32_bf16 v[24:27], v[152:155], v[194:197], v[24:27]
	v_mfma_f32_16x16x32_bf16 v[12:15], v[138:141], v[214:217], v[12:15]
	v_mfma_f32_16x16x32_bf16 v[8:11], v[152:155], v[214:217], v[8:11]
	v_mfma_f32_16x16x32_bf16 v[60:63], v[148:151], v[180:183], v[60:63]
	v_mfma_f32_16x16x32_bf16 v[56:59], v[156:159], v[180:183], v[56:59]
	v_mfma_f32_16x16x32_bf16 v[44:47], v[148:151], v[188:191], v[44:47]
	v_mfma_f32_16x16x32_bf16 v[40:43], v[156:159], v[188:191], v[40:43]
	v_mfma_f32_16x16x32_bf16 v[28:31], v[148:151], v[210:213], v[28:31]
	v_mfma_f32_16x16x32_bf16 v[24:27], v[156:159], v[210:213], v[24:27]
	v_mfma_f32_16x16x32_bf16 v[12:15], v[148:151], v[218:221], v[12:15]
	v_mfma_f32_16x16x32_bf16 v[8:11], v[156:159], v[218:221], v[8:11]
	s_setprio 0
	s_setprio 1
	v_mfma_f32_16x16x32_bf16 v[52:55], v[160:163], v[176:179], v[52:55]
	v_mfma_f32_16x16x32_bf16 v[48:51], v[168:171], v[176:179], v[48:51]
	v_mfma_f32_16x16x32_bf16 v[36:39], v[160:163], v[184:187], v[36:39]
	v_mfma_f32_16x16x32_bf16 v[32:35], v[168:171], v[184:187], v[32:35]
	v_mfma_f32_16x16x32_bf16 v[20:23], v[160:163], v[194:197], v[20:23]
	v_mfma_f32_16x16x32_bf16 v[16:19], v[168:171], v[194:197], v[16:19]
	v_mfma_f32_16x16x32_bf16 v[4:7], v[160:163], v[214:217], v[4:7]
	v_mfma_f32_16x16x32_bf16 v[0:3], v[168:171], v[214:217], v[0:3]
	v_mfma_f32_16x16x32_bf16 v[52:55], v[164:167], v[180:183], v[52:55]
	v_mfma_f32_16x16x32_bf16 v[48:51], v[172:175], v[180:183], v[48:51]
	v_mfma_f32_16x16x32_bf16 v[36:39], v[164:167], v[188:191], v[36:39]
	v_mfma_f32_16x16x32_bf16 v[32:35], v[172:175], v[188:191], v[32:35]
	v_mfma_f32_16x16x32_bf16 v[20:23], v[164:167], v[210:213], v[20:23]
	v_mfma_f32_16x16x32_bf16 v[16:19], v[172:175], v[210:213], v[16:19]
	v_mfma_f32_16x16x32_bf16 v[4:7], v[164:167], v[218:221], v[4:7]
	v_mfma_f32_16x16x32_bf16 v[0:3], v[172:175], v[218:221], v[0:3]
	s_setprio 0
	s_add_i32 s25, s25, 2
	s_add_u32 s52, s52, 0x100
	s_addc_u32 s53, s53, 0
	s_add_u32 s92, s92, 0x100
	s_addc_u32 s24, s24, 0
	s_cmp_gt_u32 s25, 29
	s_barrier
	s_cbranch_scc0 .LBB0_772
	s_and_b64 vcc, exec, s[40:41]
	s_cbranch_vccz .LBB0_775
	s_barrier

; #define PG8_STAGE(bufoff, gbase, voff) do { _Pragma("unroll") for (int _i = 0; _i < 2; ++_i) _Pragma("unroll") for (int _r = 0; _r < PG8_NREP; ++_r) \
;         __builtin_amdgcn_global_load_lds((const unsigned*)((const char*)(gbase) + (voff)[_i]), (PG8_LAS unsigned*)(lds + (bufoff) + ldsw + _i * 8192), 16, 0, 0); } while (0)
; #define PG8_LDA(dst, b, h) do { _Pragma("unroll") for (int m = 0; m < 4; ++m) _Pragma("unroll") for (int k = 0; k < 2; ++k) { dst[m][k] = *(const PG8_LAS bf16x8*)(lds + PG8_SA(b, h) + aoff + m * 2048 + k * 1024); PG8_DUP((unsigned)(uintptr_t)(lds + PG8_SA(b, h) + aoff + m * 2048 + k * 1024)); } } while (0)
; #define PG8_LDB(dst, b, h) do { _Pragma("unroll") for (int n = 0; n < 2; ++n) _Pragma("unroll") for (int k = 0; k < 2; ++k) { dst[n][k] = *(const PG8_LAS bf16x8*)(lds + PG8_SB(b, h) + boff + n * 2048 + k * 1024); PG8_DUP((unsigned)(uintptr_t)(lds + PG8_SB(b, h) + boff + n * 2048 + k * 1024)); } } while (0)
; template <class Epi, class Sched, bool ALIGN_EPI = false, bool SP2 = false>
; __device__ __forceinline__ void gemm_phase(PG8_LAS unsigned char* lds, const Gemm g, const Sched& S, const Epi& E) {
;     ...
;         const bool has_next = S.next(ui + 1, nxt);
;         const char* nA = has_next ? (const char*)g.A + (size_t)nxt.pm * tstepA : cA; const char* nB = has_next ? (const char*)g.Bt + (size_t)nxt.pn * tstepB : cB;
;         for (int t = 0; t < nt; t += 2) {
;             const bool last = (t == nt - 2);
;             const char* a1 = cA + (size_t)(t + 1) * kstep;
;             const char* a2 = last ? nA : cA + (size_t)(t + 2) * kstep; const char* b2 = last ? nB : cB + (size_t)(t + 2) * kstep;
;             const char* a3 = a2 + kstep; const char* b3 = b2 + kstep;
;             if (last && has_next) S.a_ready(nxt);
;             if constexpr (SP2) {
;     ...
;             if (Epi::PERM && sizeof(Epi) && TEST_DRAIN) PG8_WAIT_V(0);
;     ...
;             PG8_LDB(B0, 0, 0); PG8_LDB(B1, 0, 1); PG8_SCHED; PG8_LDA(At, 0, 0); PG8_STAGE(PG8_SA(1, 1), a1 + hstepA, voffA);
;             PG8_WAIT_V(8); PG8_WAIT_L(0); PG8_BAR; PG8_MMA(0, 0, At, B0); PG8_MMA(0, 1, At, B1); PG8_BAR; PG8_SCHED;
;             PG8_LDA(At, 0, 1); PG8_STAGE(PG8_SB(0, 0), b2, voffB); PG8_STAGE(PG8_SB(0, 1), b2 + hstepB, voffB); PG8_STAGE(PG8_SA(0, 0), a2, voffA);
;             PG8_WAIT_V(8); PG8_WAIT_L(0); PG8_BAR; PG8_MMA(1, 0, At, B0); PG8_MMA(1, 1, At, B1); PG8_BAR; PG8_SCHED;
.LBB0_845:
	s_add_u32 s26, s52, 0xffe00080
	s_addc_u32 s27, s53, -1
	s_add_i32 s28, 0, 0x10000
	s_cmpk_eq_i32 s25, 0x7c
	s_cselect_b32 s59, s47, s27
	s_cselect_b32 s58, s86, s26
	v_add_u32_e32 v142, s28, v145
	s_cselect_b32 s55, s45, s24
	s_cselect_b32 s54, s91, s92
	s_add_i32 s29, 0, 0x14000
	ds_read_b128 v[138:141], v142
	ds_read_b128 v[148:151], v142 offset:1024
	ds_read_b128 v[152:155], v142 offset:2048
	ds_read_b128 v[156:159], v142 offset:3072
	v_add_u32_e32 v142, s29, v145
	ds_read_b128 v[160:163], v142
	ds_read_b128 v[164:167], v142 offset:1024
	ds_read_b128 v[168:171], v142 offset:2048
	ds_read_b128 v[172:175], v142 offset:3072
	v_lshl_add_u64 v[142:143], s[52:53], 0, v[134:135]
	s_add_i32 m0, s17, 0xc000
	ds_read_b128 v[176:179], v147
	ds_read_b128 v[180:183], v147 offset:1024
	ds_read_b128 v[184:187], v147 offset:2048
	ds_read_b128 v[188:191], v147 offset:3072
	ds_read_b128 v[194:197], v147 offset:4096
	ds_read_b128 v[210:213], v147 offset:5120
	ds_read_b128 v[214:217], v147 offset:6144
	ds_read_b128 v[218:221], v147 offset:7168
	global_load_lds_dwordx4 v[142:143], off
	v_lshl_add_u64 v[142:143], s[52:53], 0, v[136:137]
	s_add_i32 m0, s17, 0xe000
	s_nop 0
	global_load_lds_dwordx4 v[142:143], off
	s_waitcnt vmcnt(8)
	s_waitcnt lgkmcnt(0)
	s_barrier
	s_setprio 1
	s_waitcnt lgkmcnt(0)
	v_mfma_f32_16x16x32_bf16 v[124:127], v[138:141], v[176:179], v[124:127]
	v_mfma_f32_16x16x32_bf16 v[120:123], v[152:155], v[176:179], v[120:123]
	v_mfma_f32_16x16x32_bf16 v[108:111], v[138:141], v[184:187], v[108:111]
	v_mfma_f32_16x16x32_bf16 v[104:107], v[152:155], v[184:187], v[104:107]
	v_mfma_f32_16x16x32_bf16 v[92:95], v[138:141], v[194:197], v[92:95]
	v_mfma_f32_16x16x32_bf16 v[88:91], v[152:155], v[194:197], v[88:91]
	v_mfma_f32_16x16x32_bf16 v[76:79], v[138:141], v[214:217], v[76:79]
	v_mfma_f32_16x16x32_bf16 v[72:75], v[152:155], v[214:217], v[72:75]
	v_mfma_f32_16x16x32_bf16 v[124:127], v[148:151], v[180:183], v[124:127]
	v_mfma_f32_16x16x32_bf16 v[120:123], v[156:159], v[180:183], v[120:123]
	v_mfma_f32_16x16x32_bf16 v[108:111], v[148:151], v[188:191], v[108:111]
	v_mfma_f32_16x16x32_bf16 v[104:107], v[156:159], v[188:191], v[104:107]
	v_mfma_f32_16x16x32_bf16 v[92:95], v[148:151], v[210:213], v[92:95]
	v_mfma_f32_16x16x32_bf16 v[88:91], v[156:159], v[210:213], v[88:91]
	v_mfma_f32_16x16x32_bf16 v[76:79], v[148:151], v[218:221], v[76:79]
	v_mfma_f32_16x16x32_bf16 v[72:75], v[156:159], v[218:221], v[72:75]
	s_setprio 0
	s_setprio 1
	v_mfma_f32_16x16x32_bf16 v[116:119], v[160:163], v[176:179], v[116:119]
	v_mfma_f32_16x16x32_bf16 v[112:115], v[168:171], v[176:179], v[112:115]
	v_mfma_f32_16x16x32_bf16 v[100:103], v[160:163], v[184:187], v[100:103]
	v_mfma_f32_16x16x32_bf16 v[96:99], v[168:171], v[184:187], v[96:99]
	v_mfma_f32_16x16x32_bf16 v[84:87], v[160:163], v[194:197], v[84:87]
	v_mfma_f32_16x16x32_bf16 v[80:83], v[168:171], v[194:197], v[80:83]
	v_mfma_f32_16x16x32_bf16 v[68:71], v[160:163], v[214:217], v[68:71]
	v_mfma_f32_16x16x32_bf16 v[64:67], v[168:171], v[214:217], v[64:67]
	v_mfma_f32_16x16x32_bf16 v[116:119], v[164:167], v[180:183], v[116:119]
	v_mfma_f32_16x16x32_bf16 v[112:115], v[172:175], v[180:183], v[112:115]
	v_mfma_f32_16x16x32_bf16 v[100:103], v[164:167], v[188:191], v[100:103]
	v_mfma_f32_16x16x32_bf16 v[96:99], v[172:175], v[188:191], v[96:99]
	v_mfma_f32_16x16x32_bf16 v[84:87], v[164:167], v[210:213], v[84:87]
	v_mfma_f32_16x16x32_bf16 v[80:83], v[172:175], v[210:213], v[80:83]
	v_mfma_f32_16x16x32_bf16 v[68:71], v[164:167], v[218:221], v[68:71]
	v_mfma_f32_16x16x32_bf16 v[64:67], v[172:175], v[218:221], v[64:67]
	s_setprio 0
	s_barrier
	s_add_i32 s26, s28, s16
	v_lshl_add_u64 v[142:143], s[54:55], 0, v[192:193]
	s_mov_b32 m0, s26
	ds_read_b128 v[176:179], v147 offset:16384
	ds_read_b128 v[180:183], v147 offset:17408
	ds_read_b128 v[184:187], v147 offset:18432
	ds_read_b128 v[188:191], v147 offset:19456
	ds_read_b128 v[194:197], v147 offset:20480
	ds_read_b128 v[210:213], v147 offset:21504
	ds_read_b128 v[214:217], v147 offset:22528
	ds_read_b128 v[218:221], v147 offset:23552
	global_load_lds_dwordx4 v[142:143], off
	s_add_i32 m0, s26, 0x2000
	s_add_u32 s26, s54, 0x200000
	v_lshl_add_u64 v[200:201], s[54:55], 0, v[128:129]
	s_addc_u32 s27, s55, 0
	s_add_i32 s28, s29, s16
	global_load_lds_dwordx4 v[200:201], off
	v_lshl_add_u64 v[222:223], s[26:27], 0, v[192:193]
	s_mov_b32 m0, s28
	v_lshl_add_u64 v[224:225], s[58:59], 0, v[130:131]
	global_load_lds_dwordx4 v[222:223], off
	v_lshl_add_u64 v[222:223], s[26:27], 0, v[128:129]
	s_add_i32 m0, s28, 0x2000
	s_nop 0
	global_load_lds_dwordx4 v[222:223], off
	v_lshl_add_u64 v[222:223], s[58:59], 0, v[132:133]
	s_mov_b32 m0, s17
	s_nop 0
	global_load_lds_dwordx4 v[222:223], off
	s_mov_b32 m0, s18
	s_nop 0
	global_load_lds_dwordx4 v[224:225], off
	s_waitcnt vmcnt(8)
	s_waitcnt lgkmcnt(0)
	s_barrier
; #define PG8_STAGE(bufoff, gbase, voff) do { _Pragma("unroll") for (int _i = 0; _i < 2; ++_i) _Pragma("unroll") for (int _r = 0; _r < PG8_NREP; ++_r) \
;         __builtin_amdgcn_global_load_lds((const unsigned*)((const char*)(gbase) + (voff)[_i]), (PG8_LAS unsigned*)(lds + (bufoff) + ldsw + _i * 8192), 16, 0, 0); } while (0)
; #define PG8_LDA(dst, b, h) do { _Pragma("unroll") for (int m = 0; m < 4; ++m) _Pragma("unroll") for (int k = 0; k < 2; ++k) { dst[m][k] = *(const PG8_LAS bf16x8*)(lds + PG8_SA(b, h) + aoff + m * 2048 + k * 1024); PG8_DUP((unsigned)(uintptr_t)(lds + PG8_SA(b, h) + aoff + m * 2048 + k * 1024)); } } while (0)
; #define PG8_LDB(dst, b, h) do { _Pragma("unroll") for (int n = 0; n < 2; ++n) _Pragma("unroll") for (int k = 0; k < 2; ++k) { dst[n][k] = *(const PG8_LAS bf16x8*)(lds + PG8_SB(b, h) + boff + n * 2048 + k * 1024); PG8_DUP((unsigned)(uintptr_t)(lds + PG8_SB(b, h) + boff + n * 2048 + k * 1024)); } } while (0)
; #define PG8_MMA(ai, bj, At, Bt) do { __builtin_amdgcn_s_setprio(1); _Pragma("unroll") for (int m = 0; m < 4; ++m) _Pragma("unroll") for (int n = 0; n < 2; ++n) _Pragma("unroll") for (int k = 0; k < 2; ++k) \
;         acc[ai][bj][m][n] = __builtin_amdgcn_mfma_f32_16x16x32_bf16(Bt[n][k], At[m][k], acc[ai][bj][m][n], 0, 0, 0); __builtin_amdgcn_s_setprio(0); } while (0)
; #define PG8_WAIT_V(n) do { if ((n) == 0) asm volatile("s_waitcnt vmcnt(0)" ::: "memory"); else if ((n) == 2) asm volatile("s_waitcnt vmcnt(4)" ::: "memory"); else if ((n) == 4) asm volatile("s_waitcnt vmcnt(8)" ::: "memory"); \
;     else if ((n) == 6) asm volatile("s_waitcnt vmcnt(12)" ::: "memory"); else asm volatile("s_waitcnt vmcnt(16)" ::: "memory"); } while (0)
; #define PG8_WAIT_V(n) asm volatile("s_waitcnt vmcnt(" #n ")" ::: "memory")
; #define PG8_BAR __builtin_amdgcn_s_barrier()
; template <class Epi, class Sched, bool ALIGN_EPI = false, bool SP2 = false>
; __device__ __forceinline__ void gemm_phase(PG8_LAS unsigned char* lds, const Gemm g, const Sched& S, const Epi& E) {
;     ...
;             PG8_WAIT_V(8); PG8_WAIT_L(0); PG8_BAR; PG8_MMA(1, 0, At, B0); PG8_MMA(1, 1, At, B1); PG8_BAR; PG8_SCHED;
;             PG8_LDB(B0, 1, 0); PG8_LDB(B1, 1, 1); PG8_SCHED; PG8_LDA(At, 1, 0); PG8_STAGE(PG8_SA(0, 1), a2 + hstepA, voffA);
;             PG8_WAIT_V(8); PG8_WAIT_L(0); PG8_BAR; PG8_MMA(0, 0, At, B0); PG8_MMA(0, 1, At, B1); PG8_BAR; PG8_SCHED;
	s_setprio 1
	s_waitcnt lgkmcnt(0)
	v_mfma_f32_16x16x32_bf16 v[60:63], v[138:141], v[176:179], v[60:63]
	v_mfma_f32_16x16x32_bf16 v[56:59], v[152:155], v[176:179], v[56:59]
	v_mfma_f32_16x16x32_bf16 v[44:47], v[138:141], v[184:187], v[44:47]
	v_mfma_f32_16x16x32_bf16 v[40:43], v[152:155], v[184:187], v[40:43]
	v_mfma_f32_16x16x32_bf16 v[28:31], v[138:141], v[194:197], v[28:31]
	v_mfma_f32_16x16x32_bf16 v[24:27], v[152:155], v[194:197], v[24:27]
	v_mfma_f32_16x16x32_bf16 v[12:15], v[138:141], v[214:217], v[12:15]
	v_mfma_f32_16x16x32_bf16 v[8:11], v[152:155], v[214:217], v[8:11]
	v_mfma_f32_16x16x32_bf16 v[60:63], v[148:151], v[180:183], v[60:63]
	v_mfma_f32_16x16x32_bf16 v[56:59], v[156:159], v[180:183], v[56:59]
	v_mfma_f32_16x16x32_bf16 v[44:47], v[148:151], v[188:191], v[44:47]
	v_mfma_f32_16x16x32_bf16 v[40:43], v[156:159], v[188:191], v[40:43]
	v_mfma_f32_16x16x32_bf16 v[28:31], v[148:151], v[210:213], v[28:31]
	v_mfma_f32_16x16x32_bf16 v[24:27], v[156:159], v[210:213], v[24:27]
	v_mfma_f32_16x16x32_bf16 v[12:15], v[148:151], v[218:221], v[12:15]
	v_mfma_f32_16x16x32_bf16 v[8:11], v[156:159], v[218:221], v[8:11]
	s_setprio 0
	s_setprio 1
	v_mfma_f32_16x16x32_bf16 v[52:55], v[160:163], v[176:179], v[52:55]
	v_mfma_f32_16x16x32_bf16 v[48:51], v[168:171], v[176:179], v[48:51]
	v_mfma_f32_16x16x32_bf16 v[36:39], v[160:163], v[184:187], v[36:39]
	v_mfma_f32_16x16x32_bf16 v[32:35], v[168:171], v[184:187], v[32:35]
	v_mfma_f32_16x16x32_bf16 v[20:23], v[160:163], v[194:197], v[20:23]
	v_mfma_f32_16x16x32_bf16 v[16:19], v[168:171], v[194:197], v[16:19]
	v_mfma_f32_16x16x32_bf16 v[4:7], v[160:163], v[214:217], v[4:7]
	v_mfma_f32_16x16x32_bf16 v[0:3], v[168:171], v[214:217], v[0:3]
	v_mfma_f32_16x16x32_bf16 v[52:55], v[164:167], v[180:183], v[52:55]
	v_mfma_f32_16x16x32_bf16 v[48:51], v[172:175], v[180:183], v[48:51]
	v_mfma_f32_16x16x32_bf16 v[36:39], v[164:167], v[188:191], v[36:39]
	v_mfma_f32_16x16x32_bf16 v[32:35], v[172:175], v[188:191], v[32:35]
	v_mfma_f32_16x16x32_bf16 v[20:23], v[164:167], v[210:213], v[20:23]
	v_mfma_f32_16x16x32_bf16 v[16:19], v[172:175], v[210:213], v[16:19]
	v_mfma_f32_16x16x32_bf16 v[4:7], v[164:167], v[218:221], v[4:7]
	v_mfma_f32_16x16x32_bf16 v[0:3], v[172:175], v[218:221], v[0:3]
	s_setprio 0
	s_barrier
	s_add_i32 s28, 0, 0x18000
	s_add_i32 s29, 0, 0x1c000
	v_add_u32_e32 v156, s28, v145
	v_add_u32_e32 v172, s29, v145
	ds_read_b128 v[138:141], v156
	ds_read_b128 v[148:151], v156 offset:1024
	ds_read_b128 v[152:155], v156 offset:2048
	ds_read_b128 v[156:159], v156 offset:3072
	ds_read_b128 v[160:163], v172
	ds_read_b128 v[164:167], v172 offset:1024
	ds_read_b128 v[168:171], v172 offset:2048
	ds_read_b128 v[172:175], v172 offset:3072
	s_add_u32 s26, s58, 0x200000
	s_addc_u32 s27, s59, 0
	s_mov_b32 m0, s19
	v_lshl_add_u64 v[226:227], s[26:27], 0, v[132:133]
	ds_read_b128 v[176:179], v147 offset:32768
	ds_read_b128 v[180:183], v147 offset:33792
	ds_read_b128 v[184:187], v147 offset:34816
	ds_read_b128 v[188:191], v147 offset:35840
	ds_read_b128 v[194:197], v147 offset:36864
	ds_read_b128 v[210:213], v147 offset:37888
	ds_read_b128 v[214:217], v147 offset:38912
	ds_read_b128 v[218:221], v147 offset:39936
	global_load_lds_dwordx4 v[226:227], off
	v_lshl_add_u64 v[226:227], s[26:27], 0, v[130:131]
	s_mov_b32 m0, s20
	s_nop 0
	global_load_lds_dwordx4 v[226:227], off
	s_waitcnt vmcnt(8)
	s_waitcnt lgkmcnt(0)
	s_barrier
	s_setprio 1
	s_waitcnt lgkmcnt(0)
	v_mfma_f32_16x16x32_bf16 v[124:127], v[138:141], v[176:179], v[124:127]
	v_mfma_f32_16x16x32_bf16 v[120:123], v[152:155], v[176:179], v[120:123]
	v_mfma_f32_16x16x32_bf16 v[108:111], v[138:141], v[184:187], v[108:111]
	v_mfma_f32_16x16x32_bf16 v[104:107], v[152:155], v[184:187], v[104:107]
	v_mfma_f32_16x16x32_bf16 v[92:95], v[138:141], v[194:197], v[92:95]
	v_mfma_f32_16x16x32_bf16 v[88:91], v[152:155], v[194:197], v[88:91]
	v_mfma_f32_16x16x32_bf16 v[76:79], v[138:141], v[214:217], v[76:79]
	v_mfma_f32_16x16x32_bf16 v[72:75], v[152:155], v[214:217], v[72:75]
	v_mfma_f32_16x16x32_bf16 v[124:127], v[148:151], v[180:183], v[124:127]
	v_mfma_f32_16x16x32_bf16 v[120:123], v[156:159], v[180:183], v[120:123]
	v_mfma_f32_16x16x32_bf16 v[108:111], v[148:151], v[188:191], v[108:111]
	v_mfma_f32_16x16x32_bf16 v[104:107], v[156:159], v[188:191], v[104:107]
	v_mfma_f32_16x16x32_bf16 v[92:95], v[148:151], v[210:213], v[92:95]
	v_mfma_f32_16x16x32_bf16 v[88:91], v[156:159], v[210:213], v[88:91]
	v_mfma_f32_16x16x32_bf16 v[76:79], v[148:151], v[218:221], v[76:79]
	v_mfma_f32_16x16x32_bf16 v[72:75], v[156:159], v[218:221], v[72:75]
	s_setprio 0
	s_setprio 1
	v_mfma_f32_16x16x32_bf16 v[116:119], v[160:163], v[176:179], v[116:119]
	v_mfma_f32_16x16x32_bf16 v[112:115], v[168:171], v[176:179], v[112:115]
	v_mfma_f32_16x16x32_bf16 v[100:103], v[160:163], v[184:187], v[100:103]
	v_mfma_f32_16x16x32_bf16 v[96:99], v[168:171], v[184:187], v[96:99]
	v_mfma_f32_16x16x32_bf16 v[84:87], v[160:163], v[194:197], v[84:87]
	v_mfma_f32_16x16x32_bf16 v[80:83], v[168:171], v[194:197], v[80:83]
	v_mfma_f32_16x16x32_bf16 v[68:71], v[160:163], v[214:217], v[68:71]
	v_mfma_f32_16x16x32_bf16 v[64:67], v[168:171], v[214:217], v[64:67]
	v_mfma_f32_16x16x32_bf16 v[116:119], v[164:167], v[180:183], v[116:119]
	v_mfma_f32_16x16x32_bf16 v[112:115], v[172:175], v[180:183], v[112:115]
	v_mfma_f32_16x16x32_bf16 v[100:103], v[164:167], v[188:191], v[100:103]
	v_mfma_f32_16x16x32_bf16 v[96:99], v[172:175], v[188:191], v[96:99]
	v_mfma_f32_16x16x32_bf16 v[84:87], v[164:167], v[210:213], v[84:87]
	v_mfma_f32_16x16x32_bf16 v[80:83], v[172:175], v[210:213], v[80:83]
	v_mfma_f32_16x16x32_bf16 v[68:71], v[164:167], v[218:221], v[68:71]
	v_mfma_f32_16x16x32_bf16 v[64:67], v[172:175], v[218:221], v[64:67]
	s_setprio 0
	s_barrier
; #define PG8_STAGE(bufoff, gbase, voff) do { _Pragma("unroll") for (int _i = 0; _i < 2; ++_i) _Pragma("unroll") for (int _r = 0; _r < PG8_NREP; ++_r) \
;         __builtin_amdgcn_global_load_lds((const unsigned*)((const char*)(gbase) + (voff)[_i]), (PG8_LAS unsigned*)(lds + (bufoff) + ldsw + _i * 8192), 16, 0, 0); } while (0)
; #define PG8_LDA(dst, b, h) do { _Pragma("unroll") for (int m = 0; m < 4; ++m) _Pragma("unroll") for (int k = 0; k < 2; ++k) { dst[m][k] = *(const PG8_LAS bf16x8*)(lds + PG8_SA(b, h) + aoff + m * 2048 + k * 1024); PG8_DUP((unsigned)(uintptr_t)(lds + PG8_SA(b, h) + aoff + m * 2048 + k * 1024)); } } while (0)
; #define PG8_MMA(ai, bj, At, Bt) do { __builtin_amdgcn_s_setprio(1); _Pragma("unroll") for (int m = 0; m < 4; ++m) _Pragma("unroll") for (int n = 0; n < 2; ++n) _Pragma("unroll") for (int k = 0; k < 2; ++k) \
;         acc[ai][bj][m][n] = __builtin_amdgcn_mfma_f32_16x16x32_bf16(Bt[n][k], At[m][k], acc[ai][bj][m][n], 0, 0, 0); __builtin_amdgcn_s_setprio(0); } while (0)
; #define PG8_WAIT_V(n) do { if ((n) == 0) asm volatile("s_waitcnt vmcnt(0)" ::: "memory"); else if ((n) == 2) asm volatile("s_waitcnt vmcnt(4)" ::: "memory"); else if ((n) == 4) asm volatile("s_waitcnt vmcnt(8)" ::: "memory"); \
;     else if ((n) == 6) asm volatile("s_waitcnt vmcnt(12)" ::: "memory"); else asm volatile("s_waitcnt vmcnt(16)" ::: "memory"); } while (0)
; #define PG8_WAIT_V(n) asm volatile("s_waitcnt vmcnt(" #n ")" ::: "memory")
; #define PG8_WAIT_L(n) asm volatile("s_waitcnt lgkmcnt(" #n ")" ::: "memory")
; #define PG8_BAR __builtin_amdgcn_s_barrier()
; #define PG8_SCHED __builtin_amdgcn_sched_barrier(0)
; template <class Epi, class Sched, bool ALIGN_EPI = false, bool SP2 = false>
; __device__ __forceinline__ void gemm_phase(PG8_LAS unsigned char* lds, const Gemm g, const Sched& S, const Epi& E) {
;     ...
;         for (int t = 0; t < nt; t += 2) {
;             const bool last = (t == nt - 2);
;             const char* a1 = cA + (size_t)(t + 1) * kstep;
;             const char* a2 = last ? nA : cA + (size_t)(t + 2) * kstep; const char* b2 = last ? nB : cB + (size_t)(t + 2) * kstep;
;     ...
;             PG8_LDA(At, 1, 1); PG8_STAGE(PG8_SB(1, 0), b3, voffB); PG8_STAGE(PG8_SB(1, 1), b3 + hstepB, voffB); PG8_STAGE(PG8_SA(1, 0), a3, voffA);
;             PG8_WAIT_V(8); PG8_WAIT_L(0); PG8_BAR; PG8_MMA(1, 0, At, B0); PG8_MMA(1, 1, At, B1); PG8_BAR; PG8_SCHED;
	s_add_i32 s26, s28, s16
	v_lshl_add_u64 v[142:143], v[142:143], 0, s[68:69]
	s_mov_b32 m0, s26
	ds_read_b128 v[176:179], v147 offset:49152
	ds_read_b128 v[180:183], v147 offset:50176
	ds_read_b128 v[184:187], v147 offset:51200
	ds_read_b128 v[188:191], v147 offset:52224
	ds_read_b128 v[194:197], v147 offset:53248
	ds_read_b128 v[210:213], v147 offset:54272
	ds_read_b128 v[214:217], v147 offset:55296
	ds_read_b128 v[218:221], v147 offset:56320
	global_load_lds_dwordx4 v[142:143], off
	s_add_i32 m0, s26, 0x2000
	s_add_u32 s26, s54, 0x200080
	v_lshl_add_u64 v[142:143], v[200:201], 0, s[68:69]
	s_addc_u32 s27, s55, 0
	s_add_i32 s28, s29, s16
	global_load_lds_dwordx4 v[142:143], off
	v_lshl_add_u64 v[142:143], s[26:27], 0, v[192:193]
	s_mov_b32 m0, s28
	s_nop 0
	global_load_lds_dwordx4 v[142:143], off
	v_lshl_add_u64 v[142:143], s[26:27], 0, v[128:129]
	s_add_i32 m0, s28, 0x2000
	s_nop 0
	global_load_lds_dwordx4 v[142:143], off
	v_lshl_add_u64 v[142:143], v[222:223], 0, s[68:69]
	s_mov_b32 m0, s21
	s_nop 0
	global_load_lds_dwordx4 v[142:143], off
	v_lshl_add_u64 v[142:143], v[224:225], 0, s[68:69]
	s_mov_b32 m0, s22
	s_nop 0
	global_load_lds_dwordx4 v[142:143], off
	s_waitcnt vmcnt(8)
	s_waitcnt lgkmcnt(0)
	s_barrier
	s_setprio 1
	s_waitcnt lgkmcnt(0)
	v_mfma_f32_16x16x32_bf16 v[60:63], v[138:141], v[176:179], v[60:63]
	v_mfma_f32_16x16x32_bf16 v[56:59], v[152:155], v[176:179], v[56:59]
	v_mfma_f32_16x16x32_bf16 v[44:47], v[138:141], v[184:187], v[44:47]
	v_mfma_f32_16x16x32_bf16 v[40:43], v[152:155], v[184:187], v[40:43]
	v_mfma_f32_16x16x32_bf16 v[28:31], v[138:141], v[194:197], v[28:31]
	v_mfma_f32_16x16x32_bf16 v[24:27], v[152:155], v[194:197], v[24:27]
	v_mfma_f32_16x16x32_bf16 v[12:15], v[138:141], v[214:217], v[12:15]
	v_mfma_f32_16x16x32_bf16 v[8:11], v[152:155], v[214:217], v[8:11]
	v_mfma_f32_16x16x32_bf16 v[60:63], v[148:151], v[180:183], v[60:63]
	v_mfma_f32_16x16x32_bf16 v[56:59], v[156:159], v[180:183], v[56:59]
	v_mfma_f32_16x16x32_bf16 v[44:47], v[148:151], v[188:191], v[44:47]
	v_mfma_f32_16x16x32_bf16 v[40:43], v[156:159], v[188:191], v[40:43]
	v_mfma_f32_16x16x32_bf16 v[28:31], v[148:151], v[210:213], v[28:31]
	v_mfma_f32_16x16x32_bf16 v[24:27], v[156:159], v[210:213], v[24:27]
	v_mfma_f32_16x16x32_bf16 v[12:15], v[148:151], v[218:221], v[12:15]
	v_mfma_f32_16x16x32_bf16 v[8:11], v[156:159], v[218:221], v[8:11]
	s_setprio 0
	s_setprio 1
	v_mfma_f32_16x16x32_bf16 v[52:55], v[160:163], v[176:179], v[52:55]
	v_mfma_f32_16x16x32_bf16 v[48:51], v[168:171], v[176:179], v[48:51]
	v_mfma_f32_16x16x32_bf16 v[36:39], v[160:163], v[184:187], v[36:39]
	v_mfma_f32_16x16x32_bf16 v[32:35], v[168:171], v[184:187], v[32:35]
	v_mfma_f32_16x16x32_bf16 v[20:23], v[160:163], v[194:197], v[20:23]
	v_mfma_f32_16x16x32_bf16 v[16:19], v[168:171], v[194:197], v[16:19]
	v_mfma_f32_16x16x32_bf16 v[4:7], v[160:163], v[214:217], v[4:7]
	v_mfma_f32_16x16x32_bf16 v[0:3], v[168:171], v[214:217], v[0:3]
	v_mfma_f32_16x16x32_bf16 v[52:55], v[164:167], v[180:183], v[52:55]
	v_mfma_f32_16x16x32_bf16 v[48:51], v[172:175], v[180:183], v[48:51]
	v_mfma_f32_16x16x32_bf16 v[36:39], v[164:167], v[188:191], v[36:39]
	v_mfma_f32_16x16x32_bf16 v[32:35], v[172:175], v[188:191], v[32:35]
	v_mfma_f32_16x16x32_bf16 v[20:23], v[164:167], v[210:213], v[20:23]
	v_mfma_f32_16x16x32_bf16 v[16:19], v[172:175], v[210:213], v[16:19]
	v_mfma_f32_16x16x32_bf16 v[4:7], v[164:167], v[218:221], v[4:7]
	v_mfma_f32_16x16x32_bf16 v[0:3], v[172:175], v[218:221], v[0:3]
	s_setprio 0
	s_add_i32 s25, s25, 2
	s_add_u32 s52, s52, 0x100
	s_addc_u32 s53, s53, 0
	s_add_u32 s92, s92, 0x100
	s_addc_u32 s24, s24, 0
	s_cmpk_gt_u32 s25, 0x7d
	s_barrier
	s_cbranch_scc0 .LBB0_845
	s_and_b64 vcc, exec, s[42:43]
	s_cbranch_vccz .LBB0_848
	s_barrier
